# P0 stores write-through too; barrier 0 drops buffer_wbl2 (on top of P2,P6,P9,P13)
# baseline (speedup 1.0000x reference)
.LBB0_21:
	s_cmpk_gt_i32 s38, 0x1ff
	s_mov_b64 s[4:5], -1
	s_cbranch_scc0 .LBB0_123
	s_cmpk_gt_u32 s38, 0x57f
	s_cbranch_scc0 .LBB0_96
	s_cmpk_gt_u32 s38, 0x5df
	s_cbranch_scc0 .LBB0_89
	s_cmpk_gt_u32 s38, 0x6df
	s_cbranch_scc0 .LBB0_62
	s_cmpk_gt_u32 s38, 0x8df
	s_cbranch_scc0 .LBB0_59
	s_cmpk_gt_u32 s38, 0xcdf
	s_cbranch_scc0 .LBB0_56
	s_cmpk_gt_u32 s38, 0x22df
	s_cbranch_scc0 .LBB0_29
	s_add_i32 s4, s38, 0xffffdd20
	s_add_i32 s5, s38, 0xffffd7a0
	s_cmpk_lt_u32 s4, 0x580
	v_mov_b32_e32 v7, s0
	v_mov_b32_e32 v8, s1
	s_cselect_b32 s20, s4, s5
	s_cmpk_gt_u32 s4, 0x57f
	v_mov_b32_e32 v4, s0
	v_readfirstlane_b32 s4, v7
	v_readfirstlane_b32 s5, v8
	s_load_dwordx2 s[4:5], s[4:5], 0xb0
	v_mov_b32_e32 v6, s1
	s_cselect_b32 s8, 0xb00000, 0
	v_readfirstlane_b32 s18, v4
	v_readfirstlane_b32 s19, v6
	s_load_dwordx2 s[18:19], s[18:19], 0xc0
	s_cselect_b32 s21, 0x580000, 0
	s_waitcnt lgkmcnt(0)
	s_add_u32 s22, s4, s8
	s_addc_u32 s23, s5, 0
	s_lshl_b32 s4, s20, 1
	s_and_b32 s8, s4, 0xfc0
	s_lshl_b32 s4, s20, 5
	s_and_b32 s4, s4, 0x3e0
	s_add_u32 s18, s18, s21
	s_addc_u32 s5, s19, 0
	s_lshl_b32 s19, s4, 2
	s_add_u32 s20, s22, s19
	v_or_b32_e32 v8, s8, v3
	s_addc_u32 s21, s23, 0
	v_lshlrev_b32_e32 v4, 2, v0
	v_lshl_add_u64 v[6:7], s[20:21], 0, v[4:5]
	v_lshlrev_b32_e32 v4, 12, v8
	v_lshl_add_u64 v[6:7], v[6:7], 0, v[4:5]
	v_add_co_u32_e32 v8, vcc, s35, v6
	s_lshl_b32 s8, s8, 1
	s_nop 0
	v_addc_co_u32_e32 v9, vcc, 0, v7, vcc
	v_add_co_u32_e32 v10, vcc, s36, v6
	s_add_u32 s18, s18, s8
	s_nop 0
	v_addc_co_u32_e32 v11, vcc, 0, v7, vcc
	v_add_co_u32_e32 v12, vcc, s37, v6
	s_addc_u32 s19, s5, 0
	s_nop 0
	v_addc_co_u32_e32 v13, vcc, 0, v7, vcc
	v_add_co_u32_e32 v14, vcc, s74, v6
	s_nop 1
	v_addc_co_u32_e32 v15, vcc, 0, v7, vcc
	v_add_co_u32_e32 v16, vcc, s39, v6
	s_nop 1
	v_addc_co_u32_e32 v17, vcc, 0, v7, vcc
	v_add_co_u32_e32 v18, vcc, s40, v6
	s_nop 1
	v_addc_co_u32_e32 v19, vcc, 0, v7, vcc
	v_add_co_u32_e32 v20, vcc, s41, v6
	s_nop 1
	v_addc_co_u32_e32 v21, vcc, 0, v7, vcc
	global_load_dword v4, v[6:7], off
	global_load_dword v24, v[8:9], off
	global_load_dword v25, v[10:11], off
	global_load_dword v81, v[12:13], off
	global_load_dword v82, v[14:15], off
	global_load_dword v83, v[16:17], off
	global_load_dword v84, v[18:19], off
	global_load_dword v85, v[20:21], off
	v_add_co_u32_e32 v8, vcc, s42, v6
	s_nop 1
	v_addc_co_u32_e32 v9, vcc, 0, v7, vcc
	v_add_co_u32_e32 v10, vcc, s43, v6
	s_nop 1
	v_addc_co_u32_e32 v11, vcc, 0, v7, vcc
	v_add_co_u32_e32 v12, vcc, s44, v6
	s_nop 1
	v_addc_co_u32_e32 v13, vcc, 0, v7, vcc
	v_add_co_u32_e32 v14, vcc, s45, v6
	s_nop 1
	v_addc_co_u32_e32 v15, vcc, 0, v7, vcc
	v_add_co_u32_e32 v16, vcc, s46, v6
	s_nop 1
	v_addc_co_u32_e32 v17, vcc, 0, v7, vcc
	v_add_co_u32_e32 v18, vcc, s47, v6
	s_nop 1
	v_addc_co_u32_e32 v19, vcc, 0, v7, vcc
	v_add_co_u32_e32 v20, vcc, s48, v6
	s_nop 1
	v_addc_co_u32_e32 v21, vcc, 0, v7, vcc
	v_add_co_u32_e32 v22, vcc, s49, v6
	s_nop 1
	v_addc_co_u32_e32 v23, vcc, 0, v7, vcc
	global_load_dword v87, v[8:9], off
	global_load_dword v88, v[10:11], off
	global_load_dword v89, v[12:13], off
	global_load_dword v90, v[14:15], off
	global_load_dword v91, v[16:17], off
	global_load_dword v92, v[18:19], off
	global_load_dword v93, v[20:21], off
	global_load_dword v94, v[22:23], off
	v_add_co_u32_e32 v8, vcc, s50, v6
	s_nop 1
	v_addc_co_u32_e32 v9, vcc, 0, v7, vcc
	v_add_co_u32_e32 v10, vcc, s51, v6
	s_nop 1
	v_addc_co_u32_e32 v11, vcc, 0, v7, vcc
	v_add_co_u32_e32 v12, vcc, s52, v6
	s_nop 1
	v_addc_co_u32_e32 v13, vcc, 0, v7, vcc
	v_add_co_u32_e32 v14, vcc, s53, v6
	s_nop 1
	v_addc_co_u32_e32 v15, vcc, 0, v7, vcc
	v_add_co_u32_e32 v16, vcc, s54, v6
	s_nop 1
	v_addc_co_u32_e32 v17, vcc, 0, v7, vcc
	v_add_co_u32_e32 v18, vcc, s55, v6
	s_nop 1
	v_addc_co_u32_e32 v19, vcc, 0, v7, vcc
	v_add_co_u32_e32 v20, vcc, s56, v6
	s_nop 1
	v_addc_co_u32_e32 v21, vcc, 0, v7, vcc
	v_add_co_u32_e32 v22, vcc, s57, v6
	s_nop 1
	v_addc_co_u32_e32 v23, vcc, 0, v7, vcc
	global_load_dword v95, v[8:9], off
	global_load_dword v96, v[10:11], off
	global_load_dword v97, v[12:13], off
	global_load_dword v98, v[14:15], off
	global_load_dword v99, v[16:17], off
	global_load_dword v100, v[18:19], off
	global_load_dword v101, v[20:21], off
	s_nop 0
	global_load_dword v22, v[22:23], off
	v_add_co_u32_e32 v8, vcc, s58, v6
	s_nop 1
	v_addc_co_u32_e32 v9, vcc, 0, v7, vcc
	v_add_co_u32_e32 v10, vcc, s59, v6
	s_nop 1
	v_addc_co_u32_e32 v11, vcc, 0, v7, vcc
	v_add_co_u32_e32 v12, vcc, s60, v6
	s_nop 1
	v_addc_co_u32_e32 v13, vcc, 0, v7, vcc
	v_add_co_u32_e32 v14, vcc, s61, v6
	s_nop 1
	v_addc_co_u32_e32 v15, vcc, 0, v7, vcc
	v_add_co_u32_e32 v16, vcc, s62, v6
	s_nop 1
	v_addc_co_u32_e32 v17, vcc, 0, v7, vcc
	v_add_co_u32_e32 v18, vcc, s63, v6
	s_nop 1
	v_addc_co_u32_e32 v19, vcc, 0, v7, vcc
	v_add_co_u32_e32 v20, vcc, s64, v6
	s_nop 1
	v_addc_co_u32_e32 v21, vcc, 0, v7, vcc
	v_add_co_u32_e32 v6, vcc, s65, v6
	s_nop 1
	v_addc_co_u32_e32 v7, vcc, 0, v7, vcc
	global_load_dword v8, v[8:9], off
	s_nop 0
	global_load_dword v9, v[10:11], off
	s_nop 0
	global_load_dword v10, v[12:13], off
	global_load_dword v11, v[14:15], off
	s_nop 0
	global_load_dword v12, v[16:17], off
	global_load_dword v13, v[18:19], off
	global_load_dword v14, v[20:21], off
	s_nop 0
	global_load_dword v6, v[6:7], off
	s_waitcnt vmcnt(30)
	ds_write2_b32 v27, v4, v24 offset1:66
	s_waitcnt vmcnt(28)
	ds_write2_b32 v27, v25, v81 offset0:132 offset1:198
	v_add_u32_e32 v4, 0x400, v27
	s_waitcnt vmcnt(26)
	ds_write2_b32 v4, v82, v83 offset0:8 offset1:74
	s_waitcnt vmcnt(24)
	ds_write2_b32 v4, v84, v85 offset0:140 offset1:206
	v_add_u32_e32 v4, 0x800, v27
	s_waitcnt vmcnt(22)
	ds_write2_b32 v4, v87, v88 offset0:16 offset1:82
	s_waitcnt vmcnt(20)
	ds_write2_b32 v4, v89, v90 offset0:148 offset1:214
	v_add_u32_e32 v4, 0xc00, v27
	s_waitcnt vmcnt(18)
	ds_write2_b32 v4, v91, v92 offset0:24 offset1:90
	s_waitcnt vmcnt(16)
	ds_write2_b32 v4, v93, v94 offset0:156 offset1:222
	v_add_u32_e32 v4, 0x1000, v27
	s_waitcnt vmcnt(14)
	ds_write2_b32 v4, v95, v96 offset0:32 offset1:98
	s_waitcnt vmcnt(12)
	ds_write2_b32 v4, v97, v98 offset0:164 offset1:230
	v_add_u32_e32 v4, 0x1400, v27
	s_waitcnt vmcnt(10)
	ds_write2_b32 v4, v99, v100 offset0:40 offset1:106
	s_waitcnt vmcnt(8)
	ds_write2_b32 v4, v101, v22 offset0:172 offset1:238
	v_add_u32_e32 v4, 0x1800, v27
	s_waitcnt vmcnt(6)
	ds_write2_b32 v4, v8, v9 offset0:48 offset1:114
	s_waitcnt vmcnt(4)
	ds_write2_b32 v4, v10, v11 offset0:180 offset1:246
	v_add_u32_e32 v4, 0x1c00, v27
	s_waitcnt vmcnt(2)
	ds_write2_b32 v4, v12, v13 offset0:56 offset1:122
	s_waitcnt vmcnt(0)
	ds_write2_b32 v4, v14, v6 offset0:188 offset1:254
	s_waitcnt lgkmcnt(0)
	v_lshlrev_b32_e32 v4, 1, v2
	ds_read2_b32 v[6:7], v29 offset1:33
	v_lshl_add_u64 v[12:13], s[18:19], 0, v[4:5]
	v_or_b32_e32 v4, s4, v28
	s_waitcnt lgkmcnt(0)
	v_cvt_pk_bf16_f32 v6, v6, v7
	ds_read2_b32 v[8:9], v29 offset0:66 offset1:99
	s_mov_b64 s[18:19], 0x23e0000
	v_mul_u32_u24_e32 v4, 0xb00, v4
	s_waitcnt lgkmcnt(0)
	v_cvt_pk_bf16_f32 v7, v8, v9
	ds_read2_b32 v[8:9], v29 offset0:132 offset1:165
	v_lshl_add_u64 v[12:13], v[12:13], 0, s[18:19]
	v_lshlrev_b32_e32 v4, 1, v4
	s_waitcnt lgkmcnt(0)
	v_cvt_pk_bf16_f32 v8, v8, v9
	ds_read2_b32 v[10:11], v29 offset0:198 offset1:231
	s_waitcnt lgkmcnt(0)
	v_cvt_pk_bf16_f32 v9, v10, v11
	v_lshl_add_u64 v[14:15], v[12:13], 0, v[4:5]
	v_or_b32_e32 v4, s4, v30
	ds_read2_b32 v[10:11], v29 offset0:8 offset1:41
	global_store_dwordx4 v[14:15], v[6:9], off sc1
	v_mul_u32_u24_e32 v4, 0xb00, v4
	v_lshlrev_b32_e32 v4, 1, v4
	s_waitcnt lgkmcnt(0)
	v_cvt_pk_bf16_f32 v6, v10, v11
	ds_read2_b32 v[8:9], v29 offset0:74 offset1:107
	s_waitcnt lgkmcnt(0)
	v_cvt_pk_bf16_f32 v7, v8, v9
	ds_read2_b32 v[8:9], v29 offset0:140 offset1:173
	s_waitcnt lgkmcnt(0)
	v_cvt_pk_bf16_f32 v8, v8, v9
	ds_read2_b32 v[10:11], v29 offset0:206 offset1:239
	s_waitcnt lgkmcnt(0)
	v_cvt_pk_bf16_f32 v9, v10, v11
	v_lshl_add_u64 v[14:15], v[12:13], 0, v[4:5]
	v_or_b32_e32 v4, s4, v31
	ds_read2_b32 v[10:11], v29 offset0:16 offset1:49
	global_store_dwordx4 v[14:15], v[6:9], off sc1
	v_mul_u32_u24_e32 v4, 0xb00, v4
	v_lshlrev_b32_e32 v4, 1, v4
	s_waitcnt lgkmcnt(0)
	v_cvt_pk_bf16_f32 v6, v10, v11
	ds_read2_b32 v[8:9], v29 offset0:82 offset1:115
	s_waitcnt lgkmcnt(0)
	v_cvt_pk_bf16_f32 v7, v8, v9
	ds_read2_b32 v[8:9], v29 offset0:148 offset1:181
	s_waitcnt lgkmcnt(0)
	v_cvt_pk_bf16_f32 v8, v8, v9
	ds_read2_b32 v[10:11], v29 offset0:214 offset1:247
	s_waitcnt lgkmcnt(0)
	v_cvt_pk_bf16_f32 v9, v10, v11
	v_lshl_add_u64 v[14:15], v[12:13], 0, v[4:5]
	ds_read2_b32 v[10:11], v29 offset0:24 offset1:57
	global_store_dwordx4 v[14:15], v[6:9], off sc1
	v_or_b32_e32 v4, s4, v32
	v_mul_u32_u24_e32 v4, 0xb00, v4
	s_waitcnt lgkmcnt(0)
	v_cvt_pk_bf16_f32 v6, v10, v11
	ds_read2_b32 v[8:9], v29 offset0:90 offset1:123
	s_waitcnt lgkmcnt(0)
	v_cvt_pk_bf16_f32 v7, v8, v9
	ds_read2_b32 v[8:9], v29 offset0:156 offset1:189
	s_waitcnt lgkmcnt(0)
	v_cvt_pk_bf16_f32 v8, v8, v9
	ds_read2_b32 v[10:11], v29 offset0:222 offset1:255
	v_lshlrev_b32_e32 v4, 1, v4
	s_waitcnt lgkmcnt(0)
	v_cvt_pk_bf16_f32 v9, v10, v11
	v_lshl_add_u64 v[10:11], v[12:13], 0, v[4:5]
	global_store_dwordx4 v[10:11], v[6:9], off sc1
	s_waitcnt lgkmcnt(0)
	s_mov_b64 s[4:5], 0

.LBB0_54:
	s_cmpk_gt_u32 s73, 0x57
	s_cselect_b32 s4, 0xf500, 0
	s_cselect_b32 s20, 0x80, 0
	s_add_i32 s8, s4, s8
	s_and_b64 s[4:5], s[18:19], exec
	s_cselect_b32 s4, 0xb00000, 0
	s_sext_i32_i16 s5, s8
	s_waitcnt lgkmcnt(0)
	s_add_u32 s4, s22, s4
	s_addc_u32 s18, s23, 0
	s_bfe_u32 s5, s5, 0x70018
	s_add_i32 s5, s8, s5
	s_waitcnt vmcnt(4)
	ds_write2_b32 v10, v8, v9 offset0:140 offset1:206
	s_sext_i32_i16 s19, s5
	s_and_b32 s5, s5, 0xff80
	s_waitcnt lgkmcnt(0)
	s_sub_i32 s5, s8, s5
	s_waitcnt vmcnt(0)
	ds_read2_b32 v[6:7], v29 offset1:33
	s_lshl_b32 s19, s19, 1
	s_sext_i32_i16 s5, s5
	s_waitcnt lgkmcnt(0)
	v_cvt_pk_bf16_f32 v6, v6, v7
	ds_read2_b32 v[8:9], v29 offset0:66 offset1:99
	s_and_b32 s19, s19, 0xffffff00
	s_add_i32 s5, s20, s5
	s_waitcnt lgkmcnt(0)
	v_cvt_pk_bf16_f32 v7, v8, v9
	ds_read2_b32 v[8:9], v29 offset0:132 offset1:165
	s_add_i32 s8, s5, s19
	s_lshl_b32 s5, s72, 1
	s_add_u32 s4, s4, s5
	s_waitcnt lgkmcnt(0)
	v_cvt_pk_bf16_f32 v8, v8, v9
	ds_read2_b32 v[10:11], v29 offset0:198 offset1:231
	s_addc_u32 s5, s18, 0
	v_lshlrev_b32_e32 v4, 1, v2
	s_waitcnt lgkmcnt(0)
	v_cvt_pk_bf16_f32 v9, v10, v11
	v_or_b32_e32 v10, s8, v28
	v_lshl_add_u64 v[12:13], s[4:5], 0, v[4:5]
	s_mov_b64 s[4:5], 0xde0000
	v_ashrrev_i32_e32 v11, 31, v10
	v_lshl_add_u64 v[12:13], v[12:13], 0, s[4:5]
	v_lshlrev_b64 v[10:11], 11, v[10:11]
	v_lshl_add_u64 v[10:11], v[12:13], 0, v[10:11]
	ds_read2_b32 v[14:15], v29 offset0:8 offset1:41
	global_store_dwordx4 v[10:11], v[6:9], off sc1
	s_waitcnt lgkmcnt(0)
	s_nop 0
	v_cvt_pk_bf16_f32 v6, v14, v15
	ds_read2_b32 v[8:9], v29 offset0:74 offset1:107
	s_waitcnt lgkmcnt(0)
	v_cvt_pk_bf16_f32 v7, v8, v9
	ds_read2_b32 v[8:9], v29 offset0:140 offset1:173
	s_waitcnt lgkmcnt(0)
	v_cvt_pk_bf16_f32 v8, v8, v9
	ds_read2_b32 v[10:11], v29 offset0:206 offset1:239
	s_waitcnt lgkmcnt(0)
	v_cvt_pk_bf16_f32 v9, v10, v11
	v_or_b32_e32 v10, s8, v30
	v_ashrrev_i32_e32 v11, 31, v10
	v_lshlrev_b64 v[10:11], 11, v[10:11]
	ds_read2_b32 v[14:15], v29 offset0:16 offset1:49
	v_lshl_add_u64 v[10:11], v[12:13], 0, v[10:11]
	global_store_dwordx4 v[10:11], v[6:9], off sc1
	s_waitcnt lgkmcnt(0)
	s_nop 0
	v_cvt_pk_bf16_f32 v6, v14, v15
	v_or_b32_e32 v14, s8, v31
	ds_read2_b32 v[8:9], v29 offset0:82 offset1:115
	v_ashrrev_i32_e32 v15, 31, v14
	s_waitcnt lgkmcnt(0)
	v_cvt_pk_bf16_f32 v7, v8, v9
	ds_read2_b32 v[8:9], v29 offset0:148 offset1:181
	v_lshlrev_b64 v[14:15], 11, v[14:15]
	s_waitcnt lgkmcnt(0)
	v_cvt_pk_bf16_f32 v8, v8, v9
	ds_read2_b32 v[10:11], v29 offset0:214 offset1:247
	s_waitcnt lgkmcnt(0)
	v_cvt_pk_bf16_f32 v9, v10, v11
	v_lshl_add_u64 v[14:15], v[12:13], 0, v[14:15]
	ds_read2_b32 v[10:11], v29 offset0:24 offset1:57
	global_store_dwordx4 v[14:15], v[6:9], off sc1
	v_or_b32_e32 v14, s8, v32
	v_ashrrev_i32_e32 v15, 31, v14
	s_waitcnt lgkmcnt(0)
	v_cvt_pk_bf16_f32 v6, v10, v11
	ds_read2_b32 v[8:9], v29 offset0:90 offset1:123
	s_waitcnt lgkmcnt(0)
	v_cvt_pk_bf16_f32 v7, v8, v9
	ds_read2_b32 v[8:9], v29 offset0:156 offset1:189
	s_waitcnt lgkmcnt(0)
	v_cvt_pk_bf16_f32 v8, v8, v9
	ds_read2_b32 v[10:11], v29 offset0:222 offset1:255
	v_lshlrev_b64 v[14:15], 11, v[14:15]
	s_waitcnt lgkmcnt(0)
	v_cvt_pk_bf16_f32 v9, v10, v11
	v_lshl_add_u64 v[10:11], v[12:13], 0, v[14:15]
	global_store_dwordx4 v[10:11], v[6:9], off sc1
	s_waitcnt lgkmcnt(0)

.LBB0_56:
	s_andn2_b64 vcc, exec, s[4:5]
	s_cbranch_vccnz .LBB0_58
	v_mov_b32_e32 v7, s1
	v_mov_b32_e32 v8, s0
	s_add_i32 s8, s38, 0xfffff720
	v_readfirstlane_b32 s4, v8
	v_readfirstlane_b32 s5, v7
	s_load_dwordx2 s[4:5], s[4:5], 0xa0
	s_lshr_b32 s8, s8, 9
	s_lshl_b64 s[18:19], s[8:9], 22
	v_mov_b32_e32 v4, s0
	v_mov_b32_e32 v6, s1
	s_waitcnt lgkmcnt(0)
	s_add_u32 s24, s4, s18
	s_addc_u32 s19, s5, s19
	s_lshl_b64 s[22:23], s[8:9], 21
	v_readfirstlane_b32 s4, v4
	v_readfirstlane_b32 s5, v6
	s_load_dwordx2 s[20:21], s[4:5], 0xc0
	s_add_i32 s4, s7, 0xffffee40
	s_and_b32 s18, s4, 0x3c0
	s_and_b32 s4, s27, 0x3e0
	v_or_b32_e32 v8, s18, v3
	s_waitcnt lgkmcnt(0)
	s_add_u32 s8, s20, s22
	s_addc_u32 s5, s21, s23
	s_lshl_b32 s20, s4, 2
	s_add_u32 s20, s24, s20
	s_addc_u32 s21, s19, 0
	v_lshlrev_b32_e32 v4, 2, v0
	v_lshl_add_u64 v[6:7], s[20:21], 0, v[4:5]
	v_lshlrev_b32_e32 v4, 12, v8
	v_lshl_add_u64 v[6:7], v[6:7], 0, v[4:5]
	v_add_co_u32_e32 v8, vcc, s35, v6
	s_lshl_b32 s18, s18, 1
	s_nop 0
	v_addc_co_u32_e32 v9, vcc, 0, v7, vcc
	v_add_co_u32_e32 v10, vcc, s36, v6
	s_add_u32 s18, s8, s18
	s_nop 0
	v_addc_co_u32_e32 v11, vcc, 0, v7, vcc
	v_add_co_u32_e32 v12, vcc, s37, v6
	s_addc_u32 s19, s5, 0
	s_nop 0
	v_addc_co_u32_e32 v13, vcc, 0, v7, vcc
	v_add_co_u32_e32 v14, vcc, s74, v6
	s_nop 1
	v_addc_co_u32_e32 v15, vcc, 0, v7, vcc
	v_add_co_u32_e32 v16, vcc, s39, v6
	s_nop 1
	v_addc_co_u32_e32 v17, vcc, 0, v7, vcc
	v_add_co_u32_e32 v18, vcc, s40, v6
	s_nop 1
	v_addc_co_u32_e32 v19, vcc, 0, v7, vcc
	v_add_co_u32_e32 v20, vcc, s41, v6
	s_nop 1
	v_addc_co_u32_e32 v21, vcc, 0, v7, vcc
	global_load_dword v4, v[6:7], off
	global_load_dword v24, v[8:9], off
	global_load_dword v25, v[10:11], off
	global_load_dword v81, v[12:13], off
	global_load_dword v82, v[14:15], off
	global_load_dword v83, v[16:17], off
	global_load_dword v84, v[18:19], off
	global_load_dword v85, v[20:21], off
	v_add_co_u32_e32 v8, vcc, s42, v6
	s_nop 1
	v_addc_co_u32_e32 v9, vcc, 0, v7, vcc
	v_add_co_u32_e32 v10, vcc, s43, v6
	s_nop 1
	v_addc_co_u32_e32 v11, vcc, 0, v7, vcc
	v_add_co_u32_e32 v12, vcc, s44, v6
	s_nop 1
	v_addc_co_u32_e32 v13, vcc, 0, v7, vcc
	v_add_co_u32_e32 v14, vcc, s45, v6
	s_nop 1
	v_addc_co_u32_e32 v15, vcc, 0, v7, vcc
	v_add_co_u32_e32 v16, vcc, s46, v6
	s_nop 1
	v_addc_co_u32_e32 v17, vcc, 0, v7, vcc
	v_add_co_u32_e32 v18, vcc, s47, v6
	s_nop 1
	v_addc_co_u32_e32 v19, vcc, 0, v7, vcc
	v_add_co_u32_e32 v20, vcc, s48, v6
	s_nop 1
	v_addc_co_u32_e32 v21, vcc, 0, v7, vcc
	v_add_co_u32_e32 v22, vcc, s49, v6
	s_nop 1
	v_addc_co_u32_e32 v23, vcc, 0, v7, vcc
	global_load_dword v87, v[8:9], off
	global_load_dword v88, v[10:11], off
	global_load_dword v89, v[12:13], off
	global_load_dword v90, v[14:15], off
	global_load_dword v91, v[16:17], off
	global_load_dword v92, v[18:19], off
	global_load_dword v93, v[20:21], off
	global_load_dword v94, v[22:23], off
	v_add_co_u32_e32 v8, vcc, s50, v6
	s_nop 1
	v_addc_co_u32_e32 v9, vcc, 0, v7, vcc
	v_add_co_u32_e32 v10, vcc, s51, v6
	s_nop 1
	v_addc_co_u32_e32 v11, vcc, 0, v7, vcc
	v_add_co_u32_e32 v12, vcc, s52, v6
	s_nop 1
	v_addc_co_u32_e32 v13, vcc, 0, v7, vcc
	v_add_co_u32_e32 v14, vcc, s53, v6
	s_nop 1
	v_addc_co_u32_e32 v15, vcc, 0, v7, vcc
	v_add_co_u32_e32 v16, vcc, s54, v6
	s_nop 1
	v_addc_co_u32_e32 v17, vcc, 0, v7, vcc
	v_add_co_u32_e32 v18, vcc, s55, v6
	s_nop 1
	v_addc_co_u32_e32 v19, vcc, 0, v7, vcc
	v_add_co_u32_e32 v20, vcc, s56, v6
	s_nop 1
	v_addc_co_u32_e32 v21, vcc, 0, v7, vcc
	v_add_co_u32_e32 v22, vcc, s57, v6
	s_nop 1
	v_addc_co_u32_e32 v23, vcc, 0, v7, vcc
	global_load_dword v95, v[8:9], off
	global_load_dword v96, v[10:11], off
	global_load_dword v97, v[12:13], off
	global_load_dword v98, v[14:15], off
	global_load_dword v99, v[16:17], off
	global_load_dword v100, v[18:19], off
	global_load_dword v101, v[20:21], off
	s_nop 0
	global_load_dword v22, v[22:23], off
	v_add_co_u32_e32 v8, vcc, s58, v6
	s_nop 1
	v_addc_co_u32_e32 v9, vcc, 0, v7, vcc
	v_add_co_u32_e32 v10, vcc, s59, v6
	s_nop 1
	v_addc_co_u32_e32 v11, vcc, 0, v7, vcc
	v_add_co_u32_e32 v12, vcc, s60, v6
	s_nop 1
	v_addc_co_u32_e32 v13, vcc, 0, v7, vcc
	v_add_co_u32_e32 v14, vcc, s61, v6
	s_nop 1
	v_addc_co_u32_e32 v15, vcc, 0, v7, vcc
	v_add_co_u32_e32 v16, vcc, s62, v6
	s_nop 1
	v_addc_co_u32_e32 v17, vcc, 0, v7, vcc
	v_add_co_u32_e32 v18, vcc, s63, v6
	s_nop 1
	v_addc_co_u32_e32 v19, vcc, 0, v7, vcc
	v_add_co_u32_e32 v20, vcc, s64, v6
	s_nop 1
	v_addc_co_u32_e32 v21, vcc, 0, v7, vcc
	v_add_co_u32_e32 v6, vcc, s65, v6
	s_nop 1
	v_addc_co_u32_e32 v7, vcc, 0, v7, vcc
	global_load_dword v8, v[8:9], off
	s_nop 0
	global_load_dword v9, v[10:11], off
	s_nop 0
	global_load_dword v10, v[12:13], off
	global_load_dword v11, v[14:15], off
	s_nop 0
	global_load_dword v12, v[16:17], off
	global_load_dword v13, v[18:19], off
	global_load_dword v14, v[20:21], off
	s_nop 0
	global_load_dword v6, v[6:7], off
	s_waitcnt vmcnt(30)
	ds_write2_b32 v27, v4, v24 offset1:66
	s_waitcnt vmcnt(28)
	ds_write2_b32 v27, v25, v81 offset0:132 offset1:198
	v_add_u32_e32 v4, 0x400, v27
	s_waitcnt vmcnt(26)
	ds_write2_b32 v4, v82, v83 offset0:8 offset1:74
	s_waitcnt vmcnt(24)
	ds_write2_b32 v4, v84, v85 offset0:140 offset1:206
	v_add_u32_e32 v4, 0x800, v27
	s_waitcnt vmcnt(22)
	ds_write2_b32 v4, v87, v88 offset0:16 offset1:82
	s_waitcnt vmcnt(20)
	ds_write2_b32 v4, v89, v90 offset0:148 offset1:214
	v_add_u32_e32 v4, 0xc00, v27
	s_waitcnt vmcnt(18)
	ds_write2_b32 v4, v91, v92 offset0:24 offset1:90
	s_waitcnt vmcnt(16)
	ds_write2_b32 v4, v93, v94 offset0:156 offset1:222
	v_add_u32_e32 v4, 0x1000, v27
	s_waitcnt vmcnt(14)
	ds_write2_b32 v4, v95, v96 offset0:32 offset1:98
	s_waitcnt vmcnt(12)
	ds_write2_b32 v4, v97, v98 offset0:164 offset1:230
	v_add_u32_e32 v4, 0x1400, v27
	s_waitcnt vmcnt(10)
	ds_write2_b32 v4, v99, v100 offset0:40 offset1:106
	s_waitcnt vmcnt(8)
	ds_write2_b32 v4, v101, v22 offset0:172 offset1:238
	v_add_u32_e32 v4, 0x1800, v27
	s_waitcnt vmcnt(6)
	ds_write2_b32 v4, v8, v9 offset0:48 offset1:114
	s_waitcnt vmcnt(4)
	ds_write2_b32 v4, v10, v11 offset0:180 offset1:246
	v_add_u32_e32 v4, 0x1c00, v27
	s_waitcnt vmcnt(2)
	ds_write2_b32 v4, v12, v13 offset0:56 offset1:122
	s_waitcnt vmcnt(0)
	ds_write2_b32 v4, v14, v6 offset0:188 offset1:254
	s_waitcnt lgkmcnt(0)
	ds_read2_b32 v[6:7], v29 offset1:33
	v_lshlrev_b32_e32 v4, 1, v2
	s_waitcnt lgkmcnt(0)
	v_cvt_pk_bf16_f32 v6, v6, v7
	ds_read2_b32 v[8:9], v29 offset0:66 offset1:99
	v_lshl_add_u64 v[12:13], s[18:19], 0, v[4:5]
	s_mov_b64 s[18:19], 0x9e0000
	v_or_b32_e32 v4, s4, v28
	s_waitcnt lgkmcnt(0)
	v_cvt_pk_bf16_f32 v7, v8, v9
	ds_read2_b32 v[8:9], v29 offset0:132 offset1:165
	v_lshl_add_u64 v[12:13], v[12:13], 0, s[18:19]
	v_lshlrev_b32_e32 v4, 11, v4
	s_waitcnt lgkmcnt(0)
	v_cvt_pk_bf16_f32 v8, v8, v9
	ds_read2_b32 v[10:11], v29 offset0:198 offset1:231
	s_waitcnt lgkmcnt(0)
	v_cvt_pk_bf16_f32 v9, v10, v11
	v_lshl_add_u64 v[14:15], v[12:13], 0, v[4:5]
	ds_read2_b32 v[10:11], v29 offset0:8 offset1:41
	global_store_dwordx4 v[14:15], v[6:9], off sc1
	v_or_b32_e32 v4, s4, v30
	v_lshlrev_b32_e32 v4, 11, v4
	s_waitcnt lgkmcnt(0)
	v_cvt_pk_bf16_f32 v6, v10, v11
	ds_read2_b32 v[8:9], v29 offset0:74 offset1:107
	s_waitcnt lgkmcnt(0)
	v_cvt_pk_bf16_f32 v7, v8, v9
	ds_read2_b32 v[8:9], v29 offset0:140 offset1:173
	s_waitcnt lgkmcnt(0)
	v_cvt_pk_bf16_f32 v8, v8, v9
	ds_read2_b32 v[10:11], v29 offset0:206 offset1:239
	s_waitcnt lgkmcnt(0)
	v_cvt_pk_bf16_f32 v9, v10, v11
	v_lshl_add_u64 v[14:15], v[12:13], 0, v[4:5]
	ds_read2_b32 v[10:11], v29 offset0:16 offset1:49
	global_store_dwordx4 v[14:15], v[6:9], off sc1
	v_or_b32_e32 v4, s4, v31
	v_lshlrev_b32_e32 v4, 11, v4
	s_waitcnt lgkmcnt(0)
	v_cvt_pk_bf16_f32 v6, v10, v11
	ds_read2_b32 v[8:9], v29 offset0:82 offset1:115
	s_waitcnt lgkmcnt(0)
	v_cvt_pk_bf16_f32 v7, v8, v9
	ds_read2_b32 v[8:9], v29 offset0:148 offset1:181
	s_waitcnt lgkmcnt(0)
	v_cvt_pk_bf16_f32 v8, v8, v9
	ds_read2_b32 v[10:11], v29 offset0:214 offset1:247
	s_waitcnt lgkmcnt(0)
	v_cvt_pk_bf16_f32 v9, v10, v11
	v_lshl_add_u64 v[14:15], v[12:13], 0, v[4:5]
	ds_read2_b32 v[10:11], v29 offset0:24 offset1:57
	global_store_dwordx4 v[14:15], v[6:9], off sc1
	v_or_b32_e32 v4, s4, v32
	v_lshlrev_b32_e32 v4, 11, v4
	s_waitcnt lgkmcnt(0)
	v_cvt_pk_bf16_f32 v6, v10, v11
	ds_read2_b32 v[8:9], v29 offset0:90 offset1:123
	s_waitcnt lgkmcnt(0)
	v_cvt_pk_bf16_f32 v7, v8, v9
	ds_read2_b32 v[8:9], v29 offset0:156 offset1:189
	s_waitcnt lgkmcnt(0)
	v_cvt_pk_bf16_f32 v8, v8, v9
	ds_read2_b32 v[10:11], v29 offset0:222 offset1:255
	s_waitcnt lgkmcnt(0)
	v_cvt_pk_bf16_f32 v9, v10, v11
	v_lshl_add_u64 v[10:11], v[12:13], 0, v[4:5]
	global_store_dwordx4 v[10:11], v[6:9], off sc1
	s_waitcnt lgkmcnt(0)

.LBB0_59:
	s_andn2_b64 vcc, exec, s[4:5]
	s_cbranch_vccnz .LBB0_61
	v_mov_b32_e32 v7, s0
	v_mov_b32_e32 v8, s1
	v_mov_b32_e32 v4, s0
	v_readfirstlane_b32 s4, v7
	v_readfirstlane_b32 s5, v8
	v_mov_b32_e32 v7, s0
	v_mov_b32_e32 v8, s1
	v_mov_b32_e32 v6, s1
	s_load_dwordx2 s[22:23], s[4:5], 0x90
	s_and_b32 s8, s7, 0x1fc0
	v_readfirstlane_b32 s4, v7
	v_readfirstlane_b32 s5, v8
	s_load_dwordx2 s[4:5], s[4:5], 0xc0
	s_and_b32 s21, s27, 0x3e0
	v_readfirstlane_b32 s18, v4
	v_readfirstlane_b32 s19, v6
	s_load_dwordx2 s[18:19], s[18:19], 0x10
	s_addk_i32 s8, 0xf240
	s_add_i32 s20, s21, 0x200
	v_or_b32_e32 v6, s8, v3
	v_lshlrev_b32_e32 v4, 2, v0
	s_waitcnt lgkmcnt(0)
	s_add_u32 s18, s18, 0x1000
	s_addc_u32 s19, s19, 0
	s_lshl_b32 s21, s21, 2
	s_add_u32 s22, s22, s21
	s_addc_u32 s23, s23, 0
	v_lshl_add_u64 v[8:9], s[22:23], 0, v[4:5]
	v_or_b32_e32 v4, 2, v6
	v_lshlrev_b64 v[12:13], 12, v[4:5]
	v_or_b32_e32 v4, 4, v6
	v_lshlrev_b64 v[14:15], 12, v[4:5]
	v_or_b32_e32 v4, 6, v6
	v_lshlrev_b64 v[16:17], 12, v[4:5]
	v_or_b32_e32 v4, 8, v6
	v_lshlrev_b64 v[18:19], 12, v[4:5]
	v_or_b32_e32 v4, 10, v6
	v_mov_b32_e32 v7, v5
	v_lshlrev_b64 v[20:21], 12, v[4:5]
	v_or_b32_e32 v4, 12, v6
	v_lshlrev_b64 v[10:11], 12, v[6:7]
	v_lshlrev_b64 v[22:23], 12, v[4:5]
	v_or_b32_e32 v4, 14, v6
	v_lshl_add_u64 v[10:11], v[8:9], 0, v[10:11]
	v_lshlrev_b64 v[24:25], 12, v[4:5]
	v_or_b32_e32 v4, 16, v6
	v_lshl_add_u64 v[12:13], v[8:9], 0, v[12:13]
	v_lshl_add_u64 v[14:15], v[8:9], 0, v[14:15]
	v_lshl_add_u64 v[16:17], v[8:9], 0, v[16:17]
	v_lshl_add_u64 v[18:19], v[8:9], 0, v[18:19]
	v_lshl_add_u64 v[20:21], v[8:9], 0, v[20:21]
	v_lshl_add_u64 v[22:23], v[8:9], 0, v[22:23]
	v_lshl_add_u64 v[24:25], v[8:9], 0, v[24:25]
	global_load_dword v81, v[10:11], off
	global_load_dword v82, v[12:13], off
	global_load_dword v83, v[14:15], off
	global_load_dword v84, v[16:17], off
	global_load_dword v85, v[18:19], off
	global_load_dword v87, v[20:21], off
	global_load_dword v88, v[22:23], off
	global_load_dword v89, v[24:25], off
	v_lshlrev_b64 v[10:11], 12, v[4:5]
	v_or_b32_e32 v4, 18, v6
	v_lshlrev_b64 v[12:13], 12, v[4:5]
	v_or_b32_e32 v4, 20, v6
	v_lshlrev_b64 v[14:15], 12, v[4:5]
	v_or_b32_e32 v4, 22, v6
	v_lshlrev_b64 v[16:17], 12, v[4:5]
	v_or_b32_e32 v4, 24, v6
	v_lshlrev_b64 v[18:19], 12, v[4:5]
	v_or_b32_e32 v4, 26, v6
	v_lshlrev_b64 v[20:21], 12, v[4:5]
	v_or_b32_e32 v4, 28, v6
	v_lshlrev_b64 v[22:23], 12, v[4:5]
	v_or_b32_e32 v4, 30, v6
	v_lshl_add_u64 v[10:11], v[8:9], 0, v[10:11]
	v_lshlrev_b64 v[24:25], 12, v[4:5]
	v_or_b32_e32 v4, 32, v6
	v_lshl_add_u64 v[12:13], v[8:9], 0, v[12:13]
	v_lshl_add_u64 v[14:15], v[8:9], 0, v[14:15]
	v_lshl_add_u64 v[16:17], v[8:9], 0, v[16:17]
	v_lshl_add_u64 v[18:19], v[8:9], 0, v[18:19]
	v_lshl_add_u64 v[20:21], v[8:9], 0, v[20:21]
	v_lshl_add_u64 v[22:23], v[8:9], 0, v[22:23]
	v_lshl_add_u64 v[24:25], v[8:9], 0, v[24:25]
	global_load_dword v90, v[10:11], off
	global_load_dword v91, v[12:13], off
	global_load_dword v92, v[14:15], off
	global_load_dword v93, v[16:17], off
	global_load_dword v94, v[18:19], off
	global_load_dword v95, v[20:21], off
	global_load_dword v96, v[22:23], off
	global_load_dword v97, v[24:25], off
	v_lshlrev_b64 v[10:11], 12, v[4:5]
	v_or_b32_e32 v4, 34, v6
	v_lshlrev_b64 v[12:13], 12, v[4:5]
	v_or_b32_e32 v4, 36, v6
	v_lshlrev_b64 v[14:15], 12, v[4:5]
	v_or_b32_e32 v4, 38, v6
	v_lshlrev_b64 v[16:17], 12, v[4:5]
	v_or_b32_e32 v4, 40, v6
	v_lshlrev_b64 v[18:19], 12, v[4:5]
	v_or_b32_e32 v4, 42, v6
	v_lshlrev_b64 v[20:21], 12, v[4:5]
	v_or_b32_e32 v4, 44, v6
	v_lshlrev_b64 v[22:23], 12, v[4:5]
	v_or_b32_e32 v4, 46, v6
	v_lshl_add_u64 v[10:11], v[8:9], 0, v[10:11]
	v_lshlrev_b64 v[24:25], 12, v[4:5]
	v_or_b32_e32 v4, 48, v6
	v_lshl_add_u64 v[12:13], v[8:9], 0, v[12:13]
	v_lshl_add_u64 v[14:15], v[8:9], 0, v[14:15]
	v_lshl_add_u64 v[16:17], v[8:9], 0, v[16:17]
	v_lshl_add_u64 v[18:19], v[8:9], 0, v[18:19]
	v_lshl_add_u64 v[20:21], v[8:9], 0, v[20:21]
	v_lshl_add_u64 v[22:23], v[8:9], 0, v[22:23]
	v_lshl_add_u64 v[24:25], v[8:9], 0, v[24:25]
	global_load_dword v98, v[10:11], off
	global_load_dword v99, v[12:13], off
	global_load_dword v100, v[14:15], off
	global_load_dword v101, v[16:17], off
	global_load_dword v102, v[18:19], off
	global_load_dword v103, v[20:21], off
	global_load_dword v104, v[22:23], off
	global_load_dword v105, v[24:25], off
	v_lshlrev_b64 v[10:11], 12, v[4:5]
	v_or_b32_e32 v4, 50, v6
	v_lshlrev_b64 v[12:13], 12, v[4:5]
	v_or_b32_e32 v4, 52, v6
	v_lshlrev_b64 v[14:15], 12, v[4:5]
	v_or_b32_e32 v4, 54, v6
	v_lshlrev_b64 v[16:17], 12, v[4:5]
	v_or_b32_e32 v4, 56, v6
	v_lshlrev_b64 v[18:19], 12, v[4:5]
	v_or_b32_e32 v4, 58, v6
	v_lshlrev_b64 v[20:21], 12, v[4:5]
	v_or_b32_e32 v4, 60, v6
	v_lshlrev_b64 v[22:23], 12, v[4:5]
	v_or_b32_e32 v4, 62, v6
	v_lshlrev_b64 v[24:25], 12, v[4:5]
	v_lshl_add_u64 v[10:11], v[8:9], 0, v[10:11]
	v_lshl_add_u64 v[12:13], v[8:9], 0, v[12:13]
	v_lshl_add_u64 v[14:15], v[8:9], 0, v[14:15]
	v_lshl_add_u64 v[16:17], v[8:9], 0, v[16:17]
	v_lshl_add_u64 v[18:19], v[8:9], 0, v[18:19]
	v_lshl_add_u64 v[20:21], v[8:9], 0, v[20:21]
	v_lshl_add_u64 v[22:23], v[8:9], 0, v[22:23]
	v_lshl_add_u64 v[8:9], v[8:9], 0, v[24:25]
	v_or_b32_e32 v4, s8, v33
	global_load_dword v24, v[10:11], off
	global_load_dword v25, v[12:13], off
	global_load_dword v106, v[14:15], off
	global_load_dword v107, v[16:17], off
	global_load_dword v108, v[18:19], off
	global_load_dword v109, v[20:21], off
	s_nop 0
	global_load_dword v22, v[22:23], off
	s_nop 0
	global_load_dword v23, v[8:9], off
	v_lshl_add_u64 v[8:9], v[4:5], 2, s[18:19]
	v_or_b32_e32 v4, s8, v35
	v_lshl_add_u64 v[10:11], v[4:5], 2, s[18:19]
	v_or_b32_e32 v4, s8, v37
	v_lshl_add_u64 v[12:13], v[4:5], 2, s[18:19]
	v_or_b32_e32 v4, s8, v38
	v_lshl_add_u64 v[14:15], v[4:5], 2, s[18:19]
	v_or_b32_e32 v4, s8, v40
	v_lshl_add_u64 v[16:17], v[4:5], 2, s[18:19]
	v_or_b32_e32 v4, s8, v41
	v_lshl_add_u64 v[18:19], v[4:5], 2, s[18:19]
	v_or_b32_e32 v4, s8, v43
	v_lshl_add_u64 v[6:7], v[6:7], 2, s[18:19]
	v_lshl_add_u64 v[20:21], v[4:5], 2, s[18:19]
	v_or_b32_e32 v4, s8, v44
	global_load_dword v110, v[6:7], off
	global_load_dword v111, v[8:9], off
	global_load_dword v112, v[10:11], off
	global_load_dword v113, v[12:13], off
	global_load_dword v114, v[14:15], off
	global_load_dword v115, v[16:17], off
	global_load_dword v116, v[18:19], off
	global_load_dword v117, v[20:21], off
	v_lshl_add_u64 v[6:7], v[4:5], 2, s[18:19]
	v_or_b32_e32 v4, s8, v46
	v_lshl_add_u64 v[8:9], v[4:5], 2, s[18:19]
	v_or_b32_e32 v4, s8, v47
	v_lshl_add_u64 v[10:11], v[4:5], 2, s[18:19]
	v_or_b32_e32 v4, s8, v49
	v_lshl_add_u64 v[12:13], v[4:5], 2, s[18:19]
	v_or_b32_e32 v4, s8, v50
	v_lshl_add_u64 v[14:15], v[4:5], 2, s[18:19]
	v_or_b32_e32 v4, s8, v52
	v_lshl_add_u64 v[16:17], v[4:5], 2, s[18:19]
	v_or_b32_e32 v4, s8, v53
	v_lshl_add_u64 v[18:19], v[4:5], 2, s[18:19]
	v_or_b32_e32 v4, s8, v55
	v_lshl_add_u64 v[20:21], v[4:5], 2, s[18:19]
	v_or_b32_e32 v4, s8, v56
	global_load_dword v118, v[6:7], off
	global_load_dword v119, v[8:9], off
	global_load_dword v120, v[10:11], off
	global_load_dword v121, v[12:13], off
	global_load_dword v122, v[14:15], off
	global_load_dword v123, v[16:17], off
	global_load_dword v124, v[18:19], off
	global_load_dword v125, v[20:21], off
	v_lshl_add_u64 v[6:7], v[4:5], 2, s[18:19]
	v_or_b32_e32 v4, s8, v58
	v_lshl_add_u64 v[8:9], v[4:5], 2, s[18:19]
	v_or_b32_e32 v4, s8, v59
	v_lshl_add_u64 v[10:11], v[4:5], 2, s[18:19]
	v_or_b32_e32 v4, s8, v61
	v_lshl_add_u64 v[12:13], v[4:5], 2, s[18:19]
	v_or_b32_e32 v4, s8, v62
	v_lshl_add_u64 v[14:15], v[4:5], 2, s[18:19]
	v_or_b32_e32 v4, s8, v64
	v_lshl_add_u64 v[16:17], v[4:5], 2, s[18:19]
	v_or_b32_e32 v4, s8, v65
	v_lshl_add_u64 v[18:19], v[4:5], 2, s[18:19]
	v_or_b32_e32 v4, s8, v67
	v_lshl_add_u64 v[20:21], v[4:5], 2, s[18:19]
	v_or_b32_e32 v4, s8, v68
	global_load_dword v126, v[6:7], off
	global_load_dword v127, v[8:9], off
	global_load_dword v128, v[10:11], off
	global_load_dword v129, v[12:13], off
	s_nop 0
	global_load_dword v14, v[14:15], off
	s_nop 0
	global_load_dword v15, v[16:17], off
	s_nop 0
	global_load_dword v16, v[18:19], off
	global_load_dword v17, v[20:21], off
	v_lshl_add_u64 v[6:7], v[4:5], 2, s[18:19]
	v_or_b32_e32 v4, s8, v71
	global_load_dword v18, v[6:7], off
	v_lshl_add_u64 v[6:7], v[4:5], 2, s[18:19]
	v_or_b32_e32 v4, s8, v72
	v_lshl_add_u64 v[8:9], v[4:5], 2, s[18:19]
	v_or_b32_e32 v4, s8, v73
	v_lshl_add_u64 v[10:11], v[4:5], 2, s[18:19]
	v_or_b32_e32 v4, s8, v74
	v_lshl_add_u64 v[12:13], v[4:5], 2, s[18:19]
	v_or_b32_e32 v4, s8, v78
	global_load_dword v19, v[6:7], off
	global_load_dword v20, v[8:9], off
	s_nop 0
	global_load_dword v10, v[10:11], off
	s_nop 0
	global_load_dword v11, v[12:13], off
	v_lshl_add_u64 v[6:7], v[4:5], 2, s[18:19]
	v_or_b32_e32 v4, s8, v79
	v_lshl_add_u64 v[8:9], v[4:5], 2, s[18:19]
	v_or_b32_e32 v4, s8, v80
	global_load_dword v12, v[6:7], off
	s_nop 0
	global_load_dword v8, v[8:9], off
	v_lshl_add_u64 v[6:7], v[4:5], 2, s[18:19]
	global_load_dword v4, v[6:7], off
	v_add_u32_e32 v7, v26, v34
	s_lshl_b64 s[18:19], s[8:9], 1
	s_add_u32 s4, s4, s18
	s_addc_u32 s5, s5, s19
	s_waitcnt vmcnt(31)
	v_mul_f32_e32 v6, v81, v110
	ds_write_b32 v27, v6
	s_waitcnt vmcnt(30)
	v_mul_f32_e32 v6, v82, v111
	s_waitcnt vmcnt(29)
	v_mul_f32_e32 v9, v83, v112
	ds_write2_b32 v7, v6, v9 offset1:66
	s_waitcnt vmcnt(28)
	v_mul_f32_e32 v6, v84, v113
	s_waitcnt vmcnt(27)
	v_mul_f32_e32 v9, v85, v114
	ds_write2_b32 v7, v6, v9 offset0:132 offset1:198
	s_waitcnt vmcnt(26)
	v_mul_f32_e32 v6, v87, v115
	s_waitcnt vmcnt(25)
	v_mul_f32_e32 v9, v88, v116
	v_add_u32_e32 v7, 0x400, v7
	ds_write2_b32 v7, v6, v9 offset0:8 offset1:74
	s_waitcnt vmcnt(24)
	v_mul_f32_e32 v6, v89, v117
	v_add_u32_e32 v9, 0x400, v75
	s_waitcnt vmcnt(23)
	v_mul_f32_e32 v7, v90, v118
	ds_write2_b32 v75, v6, v7 offset1:66
	s_waitcnt vmcnt(22)
	v_mul_f32_e32 v6, v91, v119
	s_waitcnt vmcnt(21)
	v_mul_f32_e32 v7, v92, v120
	ds_write2_b32 v75, v6, v7 offset0:132 offset1:198
	s_waitcnt vmcnt(20)
	v_mul_f32_e32 v6, v93, v121
	s_waitcnt vmcnt(19)
	v_mul_f32_e32 v7, v94, v122
	ds_write2_b32 v9, v6, v7 offset0:8 offset1:74
	s_waitcnt vmcnt(18)
	v_mul_f32_e32 v6, v95, v123
	s_waitcnt vmcnt(17)
	v_mul_f32_e32 v7, v96, v124
	ds_write2_b32 v76, v6, v7 offset1:66
	s_waitcnt vmcnt(16)
	v_mul_f32_e32 v6, v97, v125
	v_add_u32_e32 v9, 0x400, v76
	s_waitcnt vmcnt(15)
	v_mul_f32_e32 v7, v98, v126
	ds_write2_b32 v76, v6, v7 offset0:132 offset1:198
	s_waitcnt vmcnt(14)
	v_mul_f32_e32 v6, v99, v127
	s_waitcnt vmcnt(13)
	v_mul_f32_e32 v7, v100, v128
	ds_write2_b32 v9, v6, v7 offset0:8 offset1:74
	s_waitcnt vmcnt(12)
	v_mul_f32_e32 v6, v101, v129
	s_waitcnt vmcnt(11)
	v_mul_f32_e32 v7, v102, v14
	ds_write2_b32 v77, v6, v7 offset1:66
	s_waitcnt vmcnt(10)
	v_mul_f32_e32 v6, v103, v15
	s_waitcnt vmcnt(9)
	v_mul_f32_e32 v7, v104, v16
	ds_write2_b32 v77, v6, v7 offset0:132 offset1:198
	s_waitcnt vmcnt(8)
	v_mul_f32_e32 v6, v105, v17
	s_waitcnt vmcnt(7)
	v_mul_f32_e32 v7, v24, v18
	v_add_u32_e32 v9, 0x400, v77
	ds_write2_b32 v9, v6, v7 offset0:8 offset1:74
	v_add_u32_e32 v7, v26, v69
	s_waitcnt vmcnt(6)
	v_mul_f32_e32 v6, v25, v19
	s_waitcnt vmcnt(5)
	v_mul_f32_e32 v9, v106, v20
	ds_write2_b32 v7, v6, v9 offset0:66 offset1:132
	s_waitcnt vmcnt(4)
	v_mul_f32_e32 v6, v107, v10
	s_waitcnt vmcnt(3)
	v_mul_f32_e32 v9, v108, v11
	v_add_u32_e32 v10, 0x200, v7
	ds_write2_b32 v10, v6, v9 offset0:70 offset1:136
	s_waitcnt vmcnt(2)
	v_mul_f32_e32 v6, v109, v12
	s_waitcnt vmcnt(1)
	v_mul_f32_e32 v8, v22, v8
	v_add_u32_e32 v9, 0x400, v7
	s_waitcnt vmcnt(0)
	v_mul_f32_e32 v4, v23, v4
	ds_write2_b32 v9, v6, v8 offset0:74 offset1:140
	ds_write_b32 v7, v4 offset:1848
	s_waitcnt lgkmcnt(0)
	ds_read2_b32 v[6:7], v29 offset1:33
	v_lshlrev_b32_e32 v4, 1, v2
	s_waitcnt lgkmcnt(0)
	v_cvt_pk_bf16_f32 v6, v6, v7
	ds_read2_b32 v[8:9], v29 offset0:66 offset1:99
	v_lshl_add_u64 v[12:13], s[4:5], 0, v[4:5]
	v_or_b32_e32 v4, s20, v28
	s_waitcnt lgkmcnt(0)
	v_cvt_pk_bf16_f32 v7, v8, v9
	ds_read2_b32 v[8:9], v29 offset0:132 offset1:165
	v_lshl_add_u64 v[12:13], v[12:13], 0, s[10:11]
	v_lshlrev_b32_e32 v4, 11, v4
	s_waitcnt lgkmcnt(0)
	v_cvt_pk_bf16_f32 v8, v8, v9
	ds_read2_b32 v[10:11], v29 offset0:198 offset1:231
	s_waitcnt lgkmcnt(0)
	v_cvt_pk_bf16_f32 v9, v10, v11
	v_lshl_add_u64 v[14:15], v[12:13], 0, v[4:5]
	ds_read2_b32 v[10:11], v29 offset0:8 offset1:41
	global_store_dwordx4 v[14:15], v[6:9], off sc1
	v_or_b32_e32 v4, s20, v30
	v_lshlrev_b32_e32 v4, 11, v4
	s_waitcnt lgkmcnt(0)
	v_cvt_pk_bf16_f32 v6, v10, v11
	ds_read2_b32 v[8:9], v29 offset0:74 offset1:107
	s_waitcnt lgkmcnt(0)
	v_cvt_pk_bf16_f32 v7, v8, v9
	ds_read2_b32 v[8:9], v29 offset0:140 offset1:173
	s_waitcnt lgkmcnt(0)
	v_cvt_pk_bf16_f32 v8, v8, v9
	ds_read2_b32 v[10:11], v29 offset0:206 offset1:239
	s_waitcnt lgkmcnt(0)
	v_cvt_pk_bf16_f32 v9, v10, v11
	v_lshl_add_u64 v[14:15], v[12:13], 0, v[4:5]
	ds_read2_b32 v[10:11], v29 offset0:16 offset1:49
	global_store_dwordx4 v[14:15], v[6:9], off sc1
	v_or_b32_e32 v4, s20, v31
	v_lshlrev_b32_e32 v4, 11, v4
	s_waitcnt lgkmcnt(0)
	v_cvt_pk_bf16_f32 v6, v10, v11
	ds_read2_b32 v[8:9], v29 offset0:82 offset1:115
	s_waitcnt lgkmcnt(0)
	v_cvt_pk_bf16_f32 v7, v8, v9
	ds_read2_b32 v[8:9], v29 offset0:148 offset1:181
	s_waitcnt lgkmcnt(0)
	v_cvt_pk_bf16_f32 v8, v8, v9
	ds_read2_b32 v[10:11], v29 offset0:214 offset1:247
	s_waitcnt lgkmcnt(0)
	v_cvt_pk_bf16_f32 v9, v10, v11
	v_lshl_add_u64 v[14:15], v[12:13], 0, v[4:5]
	ds_read2_b32 v[10:11], v29 offset0:24 offset1:57
	global_store_dwordx4 v[14:15], v[6:9], off sc1
	v_or_b32_e32 v4, s20, v32
	v_lshlrev_b32_e32 v4, 11, v4
	s_waitcnt lgkmcnt(0)
	v_cvt_pk_bf16_f32 v6, v10, v11
	ds_read2_b32 v[8:9], v29 offset0:90 offset1:123
	s_waitcnt lgkmcnt(0)
	v_cvt_pk_bf16_f32 v7, v8, v9
	ds_read2_b32 v[8:9], v29 offset0:156 offset1:189
	s_waitcnt lgkmcnt(0)
	v_cvt_pk_bf16_f32 v8, v8, v9
	ds_read2_b32 v[10:11], v29 offset0:222 offset1:255
	s_waitcnt lgkmcnt(0)
	v_cvt_pk_bf16_f32 v9, v10, v11
	v_lshl_add_u64 v[10:11], v[12:13], 0, v[4:5]
	global_store_dwordx4 v[10:11], v[6:9], off sc1
	s_waitcnt lgkmcnt(0)

.LBB0_87:
	ds_write2_b32 v4, v8, v9 offset0:140 offset1:206
	s_lshl_b64 s[4:5], s[8:9], 1
	s_waitcnt lgkmcnt(0)
	s_waitcnt lgkmcnt(0)
	s_add_u32 s4, s18, s4
	s_waitcnt vmcnt(0)
	ds_read2_b32 v[6:7], v29 offset1:33
	v_lshlrev_b32_e32 v4, 1, v2
	s_addc_u32 s5, s19, s5
	s_waitcnt lgkmcnt(0)
	v_cvt_pk_bf16_f32 v6, v6, v7
	ds_read2_b32 v[8:9], v29 offset0:66 offset1:99
	v_or_b32_e32 v14, s72, v28
	v_lshl_add_u64 v[12:13], s[4:5], 0, v[4:5]
	s_waitcnt lgkmcnt(0)
	v_cvt_pk_bf16_f32 v7, v8, v9
	ds_read2_b32 v[8:9], v29 offset0:132 offset1:165
	v_lshlrev_b32_e32 v4, 11, v14
	v_lshl_add_u64 v[12:13], v[12:13], 0, s[10:11]
	s_waitcnt lgkmcnt(0)
	v_cvt_pk_bf16_f32 v8, v8, v9
	ds_read2_b32 v[10:11], v29 offset0:198 offset1:231
	s_waitcnt lgkmcnt(0)
	v_cvt_pk_bf16_f32 v9, v10, v11
	v_lshl_add_u64 v[14:15], v[12:13], 0, v[4:5]
	ds_read2_b32 v[10:11], v29 offset0:8 offset1:41
	global_store_dwordx4 v[14:15], v[6:9], off sc1
	v_or_b32_e32 v4, s72, v30
	v_lshlrev_b32_e32 v4, 11, v4
	s_waitcnt lgkmcnt(0)
	v_cvt_pk_bf16_f32 v6, v10, v11
	ds_read2_b32 v[8:9], v29 offset0:74 offset1:107
	s_waitcnt lgkmcnt(0)
	v_cvt_pk_bf16_f32 v7, v8, v9
	ds_read2_b32 v[8:9], v29 offset0:140 offset1:173
	s_waitcnt lgkmcnt(0)
	v_cvt_pk_bf16_f32 v8, v8, v9
	ds_read2_b32 v[10:11], v29 offset0:206 offset1:239
	s_waitcnt lgkmcnt(0)
	v_cvt_pk_bf16_f32 v9, v10, v11
	v_lshl_add_u64 v[14:15], v[12:13], 0, v[4:5]
	ds_read2_b32 v[10:11], v29 offset0:16 offset1:49
	global_store_dwordx4 v[14:15], v[6:9], off sc1
	v_or_b32_e32 v4, s72, v31
	v_lshlrev_b32_e32 v4, 11, v4
	s_waitcnt lgkmcnt(0)
	v_cvt_pk_bf16_f32 v6, v10, v11
	ds_read2_b32 v[8:9], v29 offset0:82 offset1:115
	s_waitcnt lgkmcnt(0)
	v_cvt_pk_bf16_f32 v7, v8, v9
	ds_read2_b32 v[8:9], v29 offset0:148 offset1:181
	s_waitcnt lgkmcnt(0)
	v_cvt_pk_bf16_f32 v8, v8, v9
	ds_read2_b32 v[10:11], v29 offset0:214 offset1:247
	s_waitcnt lgkmcnt(0)
	v_cvt_pk_bf16_f32 v9, v10, v11
	v_lshl_add_u64 v[14:15], v[12:13], 0, v[4:5]
	ds_read2_b32 v[10:11], v29 offset0:24 offset1:57
	global_store_dwordx4 v[14:15], v[6:9], off sc1
	v_or_b32_e32 v4, s72, v32
	v_lshlrev_b32_e32 v4, 11, v4
	s_waitcnt lgkmcnt(0)
	v_cvt_pk_bf16_f32 v6, v10, v11
	ds_read2_b32 v[8:9], v29 offset0:90 offset1:123
	s_waitcnt lgkmcnt(0)
	v_cvt_pk_bf16_f32 v7, v8, v9
	ds_read2_b32 v[8:9], v29 offset0:156 offset1:189
	s_waitcnt lgkmcnt(0)
	v_cvt_pk_bf16_f32 v8, v8, v9
	ds_read2_b32 v[10:11], v29 offset0:222 offset1:255
	s_waitcnt lgkmcnt(0)
	v_cvt_pk_bf16_f32 v9, v10, v11
	v_lshl_add_u64 v[10:11], v[12:13], 0, v[4:5]
	global_store_dwordx4 v[10:11], v[6:9], off sc1
	s_waitcnt lgkmcnt(0)

.LBB0_94:
	s_lshr_b32 s8, s20, 3
	s_add_i32 s23, s8, -6
	s_and_b64 s[4:5], exec, s[4:5]
	s_cselect_b32 s8, s8, s23
	s_add_u32 s4, s21, s18
	s_addc_u32 s5, s22, s19
	s_load_dwordx2 s[4:5], s[4:5], 0x0
	v_mov_b32_e32 v4, s0
	v_mov_b32_e32 v6, s1
	s_lshl_b64 s[18:19], s[8:9], 16
	v_readfirstlane_b32 s22, v4
	v_readfirstlane_b32 s23, v6
	s_load_dwordx2 s[22:23], s[22:23], 0xc0
	s_waitcnt lgkmcnt(0)
	s_add_u32 s8, s4, s18
	s_addc_u32 s5, s5, s19
	s_and_b32 s21, s31, 64
	s_and_b32 s24, s27, 0x60
	s_add_u32 s22, s22, s18
	s_addc_u32 s23, s23, s19
	s_cmp_gt_u32 s20, 47
	s_cselect_b32 s4, 0x80, 0
	s_or_b32 s4, s4, s24
	s_lshl_b32 s18, s24, 2
	s_add_u32 s18, s8, s18
	v_or_b32_e32 v8, s21, v3
	s_addc_u32 s19, s5, 0
	v_lshlrev_b32_e32 v4, 2, v0
	v_lshl_add_u64 v[6:7], s[18:19], 0, v[4:5]
	v_lshlrev_b32_e32 v4, 9, v8
	v_lshl_add_u64 v[6:7], v[6:7], 0, v[4:5]
	s_movk_i32 s5, 0x1000
	v_add_co_u32_e32 v8, vcc, s5, v6
	v_add_u32_e32 v94, 0x800, v27
	s_nop 0
	v_addc_co_u32_e32 v9, vcc, 0, v7, vcc
	v_add_co_u32_e32 v10, vcc, s35, v6
	v_add_u32_e32 v95, 0xc00, v27
	s_nop 0
	v_addc_co_u32_e32 v11, vcc, 0, v7, vcc
	v_add_co_u32_e32 v12, vcc, s67, v6
	v_add_u32_e32 v96, 0x1000, v27
	s_nop 0
	v_addc_co_u32_e32 v13, vcc, 0, v7, vcc
	v_add_co_u32_e32 v14, vcc, s36, v6
	s_lshl_b32 s5, s21, 1
	s_nop 0
	v_addc_co_u32_e32 v15, vcc, 0, v7, vcc
	global_load_dword v4, v[6:7], off
	global_load_dword v16, v[6:7], off offset:1024
	global_load_dword v17, v[6:7], off offset:2048
	global_load_dword v18, v[6:7], off offset:3072
	global_load_dword v19, v[8:9], off offset:1024
	global_load_dword v20, v[8:9], off offset:2048
	global_load_dword v21, v[8:9], off offset:3072
	global_load_dword v22, v[12:13], off offset:1024
	global_load_dword v23, v[10:11], off offset:-4096
	global_load_dword v24, v[10:11], off
	global_load_dword v25, v[10:11], off offset:1024
	global_load_dword v81, v[10:11], off offset:2048
	global_load_dword v82, v[10:11], off offset:3072
	global_load_dword v83, v[14:15], off offset:-4096
	global_load_dword v84, v[14:15], off
	v_add_co_u32_e32 v8, vcc, s68, v6
	s_add_u32 s18, s22, s5
	s_nop 0
	v_addc_co_u32_e32 v9, vcc, 0, v7, vcc
	v_add_co_u32_e32 v10, vcc, s37, v6
	s_addc_u32 s19, s23, 0
	s_nop 0
	v_addc_co_u32_e32 v11, vcc, 0, v7, vcc
	v_add_co_u32_e32 v6, vcc, s69, v6
	global_load_dword v85, v[12:13], off offset:2048
	s_nop 0
	global_load_dword v12, v[12:13], off offset:3072
	s_nop 0
	global_load_dword v13, v[8:9], off offset:1024
	global_load_dword v87, v[8:9], off offset:2048
	s_nop 0
	global_load_dword v8, v[8:9], off offset:3072
	s_nop 0
	global_load_dword v9, v[14:15], off offset:1024
	global_load_dword v88, v[14:15], off offset:2048
	s_nop 0
	global_load_dword v14, v[14:15], off offset:3072
	s_nop 0
	global_load_dword v15, v[10:11], off offset:-4096
	global_load_dword v89, v[10:11], off
	global_load_dword v90, v[10:11], off offset:1024
	global_load_dword v91, v[10:11], off offset:2048
	s_nop 0
	global_load_dword v10, v[10:11], off offset:3072
	v_addc_co_u32_e32 v7, vcc, 0, v7, vcc
	global_load_dword v11, v[6:7], off
	global_load_dword v92, v[6:7], off offset:1024
	global_load_dword v93, v[6:7], off offset:2048
	s_nop 0
	global_load_dword v6, v[6:7], off offset:3072
	v_add_u32_e32 v7, 0x400, v27
	s_waitcnt vmcnt(30)
	ds_write2_b32 v27, v4, v16 offset1:66
	s_waitcnt vmcnt(28)
	ds_write2_b32 v27, v17, v18 offset0:132 offset1:198
	s_waitcnt vmcnt(23)
	ds_write2_b32 v7, v23, v19 offset0:8 offset1:74
	ds_write2_b32 v7, v20, v21 offset0:140 offset1:206
	s_waitcnt vmcnt(21)
	ds_write2_b32 v94, v24, v25 offset0:16 offset1:82
	s_waitcnt vmcnt(19)
	ds_write2_b32 v94, v81, v82 offset0:148 offset1:214
	s_waitcnt vmcnt(18)
	ds_write2_b32 v95, v83, v22 offset0:24 offset1:90
	s_waitcnt vmcnt(15)
	ds_write2_b32 v95, v85, v12 offset0:156 offset1:222
	s_waitcnt vmcnt(11)
	ds_write2_b32 v96, v84, v9 offset0:32 offset1:98
	s_waitcnt vmcnt(9)
	ds_write2_b32 v96, v88, v14 offset0:164 offset1:230
	v_add_u32_e32 v4, 0x1400, v27
	s_waitcnt vmcnt(8)
	ds_write2_b32 v4, v15, v13 offset0:40 offset1:106
	ds_write2_b32 v4, v87, v8 offset0:172 offset1:238
	v_add_u32_e32 v4, 0x1800, v27
	s_waitcnt vmcnt(6)
	ds_write2_b32 v4, v89, v90 offset0:48 offset1:114
	s_waitcnt vmcnt(4)
	ds_write2_b32 v4, v91, v10 offset0:180 offset1:246
	v_add_u32_e32 v4, 0x1c00, v27
	s_waitcnt vmcnt(2)
	ds_write2_b32 v4, v11, v92 offset0:56 offset1:122
	s_waitcnt vmcnt(0)
	ds_write2_b32 v4, v93, v6 offset0:188 offset1:254
	s_waitcnt lgkmcnt(0)
	ds_read2_b32 v[6:7], v29 offset1:33
	v_lshlrev_b32_e32 v4, 1, v2
	s_waitcnt lgkmcnt(0)
	v_cvt_pk_bf16_f32 v6, v6, v7
	ds_read2_b32 v[8:9], v29 offset0:66 offset1:99
	v_lshl_add_u64 v[12:13], s[18:19], 0, v[4:5]
	v_or_b32_e32 v4, s4, v28
	s_waitcnt lgkmcnt(0)
	v_cvt_pk_bf16_f32 v7, v8, v9
	ds_read2_b32 v[8:9], v29 offset0:132 offset1:165
	v_lshl_add_u64 v[12:13], v[12:13], 0, s[12:13]
	v_lshlrev_b32_e32 v4, 8, v4
	s_waitcnt lgkmcnt(0)
	v_cvt_pk_bf16_f32 v8, v8, v9
	ds_read2_b32 v[10:11], v29 offset0:198 offset1:231
	s_waitcnt lgkmcnt(0)
	v_cvt_pk_bf16_f32 v9, v10, v11
	v_lshl_add_u64 v[14:15], v[12:13], 0, v[4:5]
	ds_read2_b32 v[10:11], v29 offset0:8 offset1:41
	global_store_dwordx4 v[14:15], v[6:9], off sc1
	v_or_b32_e32 v4, s4, v30
	v_lshlrev_b32_e32 v4, 8, v4
	s_waitcnt lgkmcnt(0)
	v_cvt_pk_bf16_f32 v6, v10, v11
	ds_read2_b32 v[8:9], v29 offset0:74 offset1:107
	s_waitcnt lgkmcnt(0)
	v_cvt_pk_bf16_f32 v7, v8, v9
	ds_read2_b32 v[8:9], v29 offset0:140 offset1:173
	s_waitcnt lgkmcnt(0)
	v_cvt_pk_bf16_f32 v8, v8, v9
	ds_read2_b32 v[10:11], v29 offset0:206 offset1:239
	s_waitcnt lgkmcnt(0)
	v_cvt_pk_bf16_f32 v9, v10, v11
	v_lshl_add_u64 v[14:15], v[12:13], 0, v[4:5]
	ds_read2_b32 v[10:11], v29 offset0:16 offset1:49
	global_store_dwordx4 v[14:15], v[6:9], off sc1
	v_or_b32_e32 v4, s4, v31
	v_lshlrev_b32_e32 v4, 8, v4
	s_waitcnt lgkmcnt(0)
	v_cvt_pk_bf16_f32 v6, v10, v11
	ds_read2_b32 v[8:9], v29 offset0:82 offset1:115
	s_waitcnt lgkmcnt(0)
	v_cvt_pk_bf16_f32 v7, v8, v9
	ds_read2_b32 v[8:9], v29 offset0:148 offset1:181
	s_waitcnt lgkmcnt(0)
	v_cvt_pk_bf16_f32 v8, v8, v9
	ds_read2_b32 v[10:11], v29 offset0:214 offset1:247
	s_waitcnt lgkmcnt(0)
	v_cvt_pk_bf16_f32 v9, v10, v11
	v_lshl_add_u64 v[14:15], v[12:13], 0, v[4:5]
	ds_read2_b32 v[10:11], v29 offset0:24 offset1:57
	global_store_dwordx4 v[14:15], v[6:9], off sc1
	v_or_b32_e32 v4, s4, v32
	v_lshlrev_b32_e32 v4, 8, v4
	s_waitcnt lgkmcnt(0)
	v_cvt_pk_bf16_f32 v6, v10, v11
	ds_read2_b32 v[8:9], v29 offset0:90 offset1:123
	s_waitcnt lgkmcnt(0)
	v_cvt_pk_bf16_f32 v7, v8, v9
	ds_read2_b32 v[8:9], v29 offset0:156 offset1:189
	s_waitcnt lgkmcnt(0)
	v_cvt_pk_bf16_f32 v8, v8, v9
	ds_read2_b32 v[10:11], v29 offset0:222 offset1:255
	s_waitcnt lgkmcnt(0)
	v_cvt_pk_bf16_f32 v9, v10, v11
	v_lshl_add_u64 v[10:11], v[12:13], 0, v[4:5]
	global_store_dwordx4 v[10:11], v[6:9], off sc1
	s_waitcnt lgkmcnt(0)

.LBB0_121:
	s_lshl_b32 s4, s8, 5
	s_waitcnt vmcnt(4)
	ds_write2_b32 v10, v8, v9 offset0:140 offset1:206
	s_lshl_b32 s5, s72, 1
	s_and_b32 s8, 0xffff, s4
	s_waitcnt lgkmcnt(0)
	s_waitcnt lgkmcnt(0)
	s_add_u32 s4, s18, s5
	s_waitcnt vmcnt(0)
	ds_read2_b32 v[6:7], v29 offset1:33
	v_lshlrev_b32_e32 v4, 1, v2
	s_addc_u32 s5, s19, 0
	s_waitcnt lgkmcnt(0)
	v_cvt_pk_bf16_f32 v6, v6, v7
	ds_read2_b32 v[8:9], v29 offset0:66 offset1:99
	v_or_b32_e32 v14, s8, v28
	v_lshl_add_u64 v[12:13], s[4:5], 0, v[4:5]
	s_waitcnt lgkmcnt(0)
	v_cvt_pk_bf16_f32 v7, v8, v9
	ds_read2_b32 v[8:9], v29 offset0:132 offset1:165
	v_lshlrev_b32_e32 v4, 11, v14
	v_lshl_add_u64 v[12:13], v[12:13], 0, s[14:15]
	s_waitcnt lgkmcnt(0)
	v_cvt_pk_bf16_f32 v8, v8, v9
	ds_read2_b32 v[10:11], v29 offset0:198 offset1:231
	s_waitcnt lgkmcnt(0)
	v_cvt_pk_bf16_f32 v9, v10, v11
	v_lshl_add_u64 v[14:15], v[12:13], 0, v[4:5]
	ds_read2_b32 v[10:11], v29 offset0:8 offset1:41
	global_store_dwordx4 v[14:15], v[6:9], off sc1
	v_or_b32_e32 v4, s8, v30
	v_lshlrev_b32_e32 v4, 11, v4
	s_waitcnt lgkmcnt(0)
	v_cvt_pk_bf16_f32 v6, v10, v11
	ds_read2_b32 v[8:9], v29 offset0:74 offset1:107
	s_waitcnt lgkmcnt(0)
	v_cvt_pk_bf16_f32 v7, v8, v9
	ds_read2_b32 v[8:9], v29 offset0:140 offset1:173
	s_waitcnt lgkmcnt(0)
	v_cvt_pk_bf16_f32 v8, v8, v9
	ds_read2_b32 v[10:11], v29 offset0:206 offset1:239
	s_waitcnt lgkmcnt(0)
	v_cvt_pk_bf16_f32 v9, v10, v11
	v_lshl_add_u64 v[14:15], v[12:13], 0, v[4:5]
	ds_read2_b32 v[10:11], v29 offset0:16 offset1:49
	global_store_dwordx4 v[14:15], v[6:9], off sc1
	v_or_b32_e32 v4, s8, v31
	v_lshlrev_b32_e32 v4, 11, v4
	s_waitcnt lgkmcnt(0)
	v_cvt_pk_bf16_f32 v6, v10, v11
	ds_read2_b32 v[8:9], v29 offset0:82 offset1:115
	s_waitcnt lgkmcnt(0)
	v_cvt_pk_bf16_f32 v7, v8, v9
	ds_read2_b32 v[8:9], v29 offset0:148 offset1:181
	s_waitcnt lgkmcnt(0)
	v_cvt_pk_bf16_f32 v8, v8, v9
	ds_read2_b32 v[10:11], v29 offset0:214 offset1:247
	s_waitcnt lgkmcnt(0)
	v_cvt_pk_bf16_f32 v9, v10, v11
	v_lshl_add_u64 v[14:15], v[12:13], 0, v[4:5]
	ds_read2_b32 v[10:11], v29 offset0:24 offset1:57
	global_store_dwordx4 v[14:15], v[6:9], off sc1
	v_or_b32_e32 v4, s8, v32
	v_lshlrev_b32_e32 v4, 11, v4
	s_waitcnt lgkmcnt(0)
	v_cvt_pk_bf16_f32 v6, v10, v11
	ds_read2_b32 v[8:9], v29 offset0:90 offset1:123
	s_waitcnt lgkmcnt(0)
	v_cvt_pk_bf16_f32 v7, v8, v9
	ds_read2_b32 v[8:9], v29 offset0:156 offset1:189
	s_waitcnt lgkmcnt(0)
	v_cvt_pk_bf16_f32 v8, v8, v9
	ds_read2_b32 v[10:11], v29 offset0:222 offset1:255
	s_waitcnt lgkmcnt(0)
	v_cvt_pk_bf16_f32 v9, v10, v11
	v_lshl_add_u64 v[10:11], v[12:13], 0, v[4:5]
	global_store_dwordx4 v[10:11], v[6:9], off sc1
	s_waitcnt lgkmcnt(0)

.LBB0_123:
	s_andn2_b64 vcc, exec, s[4:5]
	s_cbranch_vccnz .LBB0_20
	s_ashr_i32 s4, s38, 31
	s_lshr_b32 s4, s4, 24
	s_add_i32 s4, s38, s4
	s_ashr_i32 s18, s4, 8
	s_and_b32 s4, s4, 0xff00
	s_sub_i32 s8, s38, s4
	s_sext_i32_i16 s4, s8
	s_bfe_u32 s4, s4, 0x4001b
	s_add_i32 s4, s8, s4
	v_mov_b32_e32 v4, s0
	v_mov_b32_e32 v6, s1
	s_sext_i32_i16 s22, s4
	s_and_b32 s19, s4, 0xfff0
	s_sub_i32 s8, s8, s19
	v_readfirstlane_b32 s4, v4
	v_readfirstlane_b32 s5, v6
	s_load_dwordx2 s[4:5], s[4:5], 0x38
	s_ashr_i32 s19, s18, 31
	s_lshl_b64 s[20:21], s[18:19], 21
	s_sext_i32_i16 s8, s8
	v_lshlrev_b32_e32 v4, 2, v0
	s_waitcnt lgkmcnt(0)
	s_add_u32 s23, s4, s20
	s_addc_u32 s5, s5, s21
	s_lshl_b32 s4, s22, 2
	s_lshl_b32 s20, s8, 5
	s_andn2_b32 s4, s4, 63
	s_lshl_b32 s8, s18, 9
	s_ashr_i32 s21, s20, 31
	s_add_i32 s8, s20, s8
	v_or_b32_e32 v6, s4, v3
	s_lshl_b64 s[18:19], s[20:21], 2
	s_add_u32 s18, s23, s18
	v_or_b32_e32 v12, 2, v6
	v_or_b32_e32 v14, 4, v6
	v_or_b32_e32 v16, 6, v6
	v_or_b32_e32 v18, 8, v6
	v_or_b32_e32 v20, 10, v6
	v_or_b32_e32 v22, 12, v6
	v_or_b32_e32 v24, 14, v6
	s_addc_u32 s19, s5, s19
	v_ashrrev_i32_e32 v7, 31, v6
	v_ashrrev_i32_e32 v13, 31, v12
	v_ashrrev_i32_e32 v15, 31, v14
	v_ashrrev_i32_e32 v17, 31, v16
	v_ashrrev_i32_e32 v19, 31, v18
	v_ashrrev_i32_e32 v21, 31, v20
	v_ashrrev_i32_e32 v23, 31, v22
	v_ashrrev_i32_e32 v25, 31, v24
	v_lshl_add_u64 v[8:9], s[18:19], 0, v[4:5]
	v_lshlrev_b64 v[10:11], 11, v[6:7]
	v_lshlrev_b64 v[12:13], 11, v[12:13]
	v_lshlrev_b64 v[14:15], 11, v[14:15]
	v_lshlrev_b64 v[16:17], 11, v[16:17]
	v_lshlrev_b64 v[18:19], 11, v[18:19]
	v_lshlrev_b64 v[20:21], 11, v[20:21]
	v_lshlrev_b64 v[22:23], 11, v[22:23]
	v_lshlrev_b64 v[24:25], 11, v[24:25]
	v_mov_b32_e32 v81, s0
	v_mov_b32_e32 v82, s1
	v_lshl_add_u64 v[10:11], v[8:9], 0, v[10:11]
	v_lshl_add_u64 v[12:13], v[8:9], 0, v[12:13]
	v_lshl_add_u64 v[14:15], v[8:9], 0, v[14:15]
	v_lshl_add_u64 v[16:17], v[8:9], 0, v[16:17]
	v_lshl_add_u64 v[18:19], v[8:9], 0, v[18:19]
	v_lshl_add_u64 v[20:21], v[8:9], 0, v[20:21]
	v_lshl_add_u64 v[22:23], v[8:9], 0, v[22:23]
	v_lshl_add_u64 v[24:25], v[8:9], 0, v[24:25]
	global_load_dword v4, v[10:11], off
	global_load_dword v83, v[12:13], off
	global_load_dword v84, v[14:15], off
	global_load_dword v85, v[16:17], off
	global_load_dword v87, v[18:19], off
	global_load_dword v88, v[20:21], off
	global_load_dword v89, v[22:23], off
	global_load_dword v90, v[24:25], off
	v_or_b32_e32 v10, 16, v6
	v_or_b32_e32 v12, 18, v6
	v_or_b32_e32 v14, 20, v6
	v_or_b32_e32 v16, 22, v6
	v_or_b32_e32 v18, 24, v6
	v_or_b32_e32 v20, 26, v6
	v_or_b32_e32 v22, 28, v6
	v_or_b32_e32 v24, 30, v6
	v_ashrrev_i32_e32 v11, 31, v10
	v_ashrrev_i32_e32 v13, 31, v12
	v_ashrrev_i32_e32 v15, 31, v14
	v_ashrrev_i32_e32 v17, 31, v16
	v_ashrrev_i32_e32 v19, 31, v18
	v_ashrrev_i32_e32 v21, 31, v20
	v_ashrrev_i32_e32 v23, 31, v22
	v_ashrrev_i32_e32 v25, 31, v24
	v_lshlrev_b64 v[10:11], 11, v[10:11]
	v_lshlrev_b64 v[12:13], 11, v[12:13]
	v_lshlrev_b64 v[14:15], 11, v[14:15]
	v_lshlrev_b64 v[16:17], 11, v[16:17]
	v_lshlrev_b64 v[18:19], 11, v[18:19]
	v_lshlrev_b64 v[20:21], 11, v[20:21]
	v_lshlrev_b64 v[22:23], 11, v[22:23]
	v_lshlrev_b64 v[24:25], 11, v[24:25]
	v_lshl_add_u64 v[10:11], v[8:9], 0, v[10:11]
	v_lshl_add_u64 v[12:13], v[8:9], 0, v[12:13]
	v_lshl_add_u64 v[14:15], v[8:9], 0, v[14:15]
	v_lshl_add_u64 v[16:17], v[8:9], 0, v[16:17]
	v_lshl_add_u64 v[18:19], v[8:9], 0, v[18:19]
	v_lshl_add_u64 v[20:21], v[8:9], 0, v[20:21]
	v_lshl_add_u64 v[22:23], v[8:9], 0, v[22:23]
	v_lshl_add_u64 v[24:25], v[8:9], 0, v[24:25]
	global_load_dword v91, v[10:11], off
	global_load_dword v92, v[12:13], off
	global_load_dword v93, v[14:15], off
	global_load_dword v94, v[16:17], off
	global_load_dword v95, v[18:19], off
	global_load_dword v96, v[20:21], off
	global_load_dword v97, v[22:23], off
	global_load_dword v98, v[24:25], off
	v_or_b32_e32 v10, 32, v6
	v_or_b32_e32 v12, 34, v6
	v_or_b32_e32 v14, 36, v6
	v_or_b32_e32 v16, 38, v6
	v_or_b32_e32 v18, 40, v6
	v_or_b32_e32 v20, 42, v6
	v_or_b32_e32 v22, 44, v6
	v_or_b32_e32 v24, 46, v6
	v_ashrrev_i32_e32 v11, 31, v10
	v_ashrrev_i32_e32 v13, 31, v12
	v_ashrrev_i32_e32 v15, 31, v14
	v_ashrrev_i32_e32 v17, 31, v16
	v_ashrrev_i32_e32 v19, 31, v18
	v_ashrrev_i32_e32 v21, 31, v20
	v_ashrrev_i32_e32 v23, 31, v22
	v_ashrrev_i32_e32 v25, 31, v24
	v_lshlrev_b64 v[10:11], 11, v[10:11]
	v_lshlrev_b64 v[12:13], 11, v[12:13]
	v_lshlrev_b64 v[14:15], 11, v[14:15]
	v_lshlrev_b64 v[16:17], 11, v[16:17]
	v_lshlrev_b64 v[18:19], 11, v[18:19]
	v_lshlrev_b64 v[20:21], 11, v[20:21]
	v_lshlrev_b64 v[22:23], 11, v[22:23]
	v_lshlrev_b64 v[24:25], 11, v[24:25]
	v_lshl_add_u64 v[10:11], v[8:9], 0, v[10:11]
	v_lshl_add_u64 v[12:13], v[8:9], 0, v[12:13]
	v_lshl_add_u64 v[14:15], v[8:9], 0, v[14:15]
	v_lshl_add_u64 v[16:17], v[8:9], 0, v[16:17]
	v_lshl_add_u64 v[18:19], v[8:9], 0, v[18:19]
	v_lshl_add_u64 v[20:21], v[8:9], 0, v[20:21]
	v_lshl_add_u64 v[22:23], v[8:9], 0, v[22:23]
	v_lshl_add_u64 v[24:25], v[8:9], 0, v[24:25]
	global_load_dword v99, v[10:11], off
	global_load_dword v100, v[12:13], off
	global_load_dword v101, v[14:15], off
	global_load_dword v102, v[16:17], off
	global_load_dword v103, v[18:19], off
	global_load_dword v104, v[20:21], off
	global_load_dword v105, v[22:23], off
	s_nop 0
	global_load_dword v24, v[24:25], off
	v_or_b32_e32 v10, 48, v6
	v_or_b32_e32 v12, 50, v6
	v_or_b32_e32 v14, 52, v6
	v_or_b32_e32 v16, 54, v6
	v_or_b32_e32 v18, 56, v6
	v_or_b32_e32 v20, 58, v6
	v_or_b32_e32 v22, 60, v6
	v_or_b32_e32 v6, 62, v6
	v_ashrrev_i32_e32 v11, 31, v10
	v_ashrrev_i32_e32 v13, 31, v12
	v_ashrrev_i32_e32 v15, 31, v14
	v_ashrrev_i32_e32 v7, 31, v6
	v_lshlrev_b64 v[10:11], 11, v[10:11]
	v_lshlrev_b64 v[12:13], 11, v[12:13]
	v_lshlrev_b64 v[14:15], 11, v[14:15]
	v_ashrrev_i32_e32 v17, 31, v16
	v_ashrrev_i32_e32 v19, 31, v18
	v_ashrrev_i32_e32 v21, 31, v20
	v_ashrrev_i32_e32 v23, 31, v22
	v_lshlrev_b64 v[6:7], 11, v[6:7]
	v_lshl_add_u64 v[10:11], v[8:9], 0, v[10:11]
	v_lshl_add_u64 v[12:13], v[8:9], 0, v[12:13]
	v_lshl_add_u64 v[14:15], v[8:9], 0, v[14:15]
	v_lshlrev_b64 v[16:17], 11, v[16:17]
	v_lshlrev_b64 v[18:19], 11, v[18:19]
	v_lshlrev_b64 v[20:21], 11, v[20:21]
	v_lshlrev_b64 v[22:23], 11, v[22:23]
	v_lshl_add_u64 v[6:7], v[8:9], 0, v[6:7]
	v_lshl_add_u64 v[16:17], v[8:9], 0, v[16:17]
	v_lshl_add_u64 v[18:19], v[8:9], 0, v[18:19]
	v_lshl_add_u64 v[20:21], v[8:9], 0, v[20:21]
	v_lshl_add_u64 v[22:23], v[8:9], 0, v[22:23]
	global_load_dword v8, v[10:11], off
	global_load_dword v9, v[12:13], off
	s_nop 0
	global_load_dword v10, v[14:15], off
	global_load_dword v11, v[16:17], off
	global_load_dword v12, v[18:19], off
	global_load_dword v13, v[20:21], off
	s_nop 0
	global_load_dword v14, v[22:23], off
	s_nop 0
	global_load_dword v6, v[6:7], off
	v_readfirstlane_b32 s18, v81
	v_readfirstlane_b32 s19, v82
	s_load_dwordx2 s[18:19], s[18:19], 0xc0
	s_waitcnt vmcnt(30)
	ds_write2_b32 v27, v4, v83 offset1:66
	s_waitcnt vmcnt(28)
	ds_write2_b32 v27, v84, v85 offset0:132 offset1:198
	v_add_u32_e32 v4, 0x400, v27
	s_waitcnt vmcnt(26)
	ds_write2_b32 v4, v87, v88 offset0:8 offset1:74
	s_waitcnt vmcnt(24)
	ds_write2_b32 v4, v89, v90 offset0:140 offset1:206
	v_add_u32_e32 v4, 0x800, v27
	s_waitcnt vmcnt(22)
	ds_write2_b32 v4, v91, v92 offset0:16 offset1:82
	s_waitcnt vmcnt(20)
	ds_write2_b32 v4, v93, v94 offset0:148 offset1:214
	v_add_u32_e32 v4, 0xc00, v27
	s_waitcnt vmcnt(18)
	ds_write2_b32 v4, v95, v96 offset0:24 offset1:90
	s_waitcnt vmcnt(16)
	ds_write2_b32 v4, v97, v98 offset0:156 offset1:222
	v_add_u32_e32 v4, 0x1000, v27
	s_waitcnt vmcnt(14)
	ds_write2_b32 v4, v99, v100 offset0:32 offset1:98
	s_waitcnt vmcnt(12)
	ds_write2_b32 v4, v101, v102 offset0:164 offset1:230
	v_add_u32_e32 v4, 0x1400, v27
	s_waitcnt vmcnt(10)
	ds_write2_b32 v4, v103, v104 offset0:40 offset1:106
	s_waitcnt vmcnt(8)
	ds_write2_b32 v4, v105, v24 offset0:172 offset1:238
	v_add_u32_e32 v4, 0x1800, v27
	s_waitcnt vmcnt(6)
	ds_write2_b32 v4, v8, v9 offset0:48 offset1:114
	s_waitcnt vmcnt(4)
	ds_write2_b32 v4, v10, v11 offset0:180 offset1:246
	v_add_u32_e32 v4, 0x1c00, v27
	s_waitcnt vmcnt(2)
	ds_write2_b32 v4, v12, v13 offset0:56 offset1:122
	s_waitcnt vmcnt(0)
	ds_write2_b32 v4, v14, v6 offset0:188 offset1:254
	s_waitcnt lgkmcnt(0)
	ds_read2_b32 v[6:7], v29 offset1:33
	s_waitcnt lgkmcnt(0)
	v_cvt_pk_bf16_f32 v6, v6, v7
	ds_read2_b32 v[8:9], v29 offset0:66 offset1:99
	s_ashr_i32 s5, s4, 31
	s_waitcnt lgkmcnt(0)
	v_cvt_pk_bf16_f32 v7, v8, v9
	ds_read2_b32 v[8:9], v29 offset0:132 offset1:165
	s_lshl_b64 s[4:5], s[4:5], 1
	s_add_u32 s4, s18, s4
	s_waitcnt lgkmcnt(0)
	v_cvt_pk_bf16_f32 v8, v8, v9
	ds_read2_b32 v[10:11], v29 offset0:198 offset1:231
	s_addc_u32 s5, s19, s5
	v_lshlrev_b32_e32 v4, 1, v2
	s_waitcnt lgkmcnt(0)
	v_cvt_pk_bf16_f32 v9, v10, v11
	v_or_b32_e32 v10, s8, v28
	v_lshl_add_u64 v[12:13], s[4:5], 0, v[4:5]
	v_ashrrev_i32_e32 v11, 31, v10
	v_lshl_add_u64 v[12:13], v[12:13], 0, s[16:17]
	v_lshlrev_b64 v[10:11], 11, v[10:11]
	v_lshl_add_u64 v[10:11], v[12:13], 0, v[10:11]
	ds_read2_b32 v[14:15], v29 offset0:8 offset1:41
	global_store_dwordx4 v[10:11], v[6:9], off sc1
	s_waitcnt lgkmcnt(0)
	s_nop 0
	v_cvt_pk_bf16_f32 v6, v14, v15
	ds_read2_b32 v[8:9], v29 offset0:74 offset1:107
	s_waitcnt lgkmcnt(0)
	v_cvt_pk_bf16_f32 v7, v8, v9
	ds_read2_b32 v[8:9], v29 offset0:140 offset1:173
	s_waitcnt lgkmcnt(0)
	v_cvt_pk_bf16_f32 v8, v8, v9
	ds_read2_b32 v[10:11], v29 offset0:206 offset1:239
	s_waitcnt lgkmcnt(0)
	v_cvt_pk_bf16_f32 v9, v10, v11
	v_or_b32_e32 v10, s8, v30
	v_ashrrev_i32_e32 v11, 31, v10
	v_lshlrev_b64 v[10:11], 11, v[10:11]
	v_lshl_add_u64 v[10:11], v[12:13], 0, v[10:11]
	ds_read2_b32 v[14:15], v29 offset0:16 offset1:49
	global_store_dwordx4 v[10:11], v[6:9], off sc1
	s_waitcnt lgkmcnt(0)
	s_nop 0
	v_cvt_pk_bf16_f32 v6, v14, v15
	ds_read2_b32 v[8:9], v29 offset0:82 offset1:115
	s_waitcnt lgkmcnt(0)
	v_cvt_pk_bf16_f32 v7, v8, v9
	ds_read2_b32 v[8:9], v29 offset0:148 offset1:181
	s_waitcnt lgkmcnt(0)
	v_cvt_pk_bf16_f32 v8, v8, v9
	ds_read2_b32 v[10:11], v29 offset0:214 offset1:247
	s_waitcnt lgkmcnt(0)
	v_cvt_pk_bf16_f32 v9, v10, v11
	v_or_b32_e32 v10, s8, v31
	v_ashrrev_i32_e32 v11, 31, v10
	v_lshlrev_b64 v[10:11], 11, v[10:11]
	v_lshl_add_u64 v[10:11], v[12:13], 0, v[10:11]
	ds_read2_b32 v[14:15], v29 offset0:24 offset1:57
	global_store_dwordx4 v[10:11], v[6:9], off sc1
	s_waitcnt lgkmcnt(0)
	s_nop 0
	v_cvt_pk_bf16_f32 v6, v14, v15
	ds_read2_b32 v[8:9], v29 offset0:90 offset1:123
	s_waitcnt lgkmcnt(0)
	v_cvt_pk_bf16_f32 v7, v8, v9
	ds_read2_b32 v[8:9], v29 offset0:156 offset1:189
	s_waitcnt lgkmcnt(0)
	v_cvt_pk_bf16_f32 v8, v8, v9
	ds_read2_b32 v[10:11], v29 offset0:222 offset1:255
	s_waitcnt lgkmcnt(0)
	v_cvt_pk_bf16_f32 v9, v10, v11
	v_or_b32_e32 v10, s8, v32
	v_ashrrev_i32_e32 v11, 31, v10
	v_lshlrev_b64 v[10:11], 11, v[10:11]
	v_lshl_add_u64 v[10:11], v[12:13], 0, v[10:11]
	global_store_dwordx4 v[10:11], v[6:9], off sc1
	s_waitcnt lgkmcnt(0)
	s_branch .LBB0_20

.LBB0_152:
	s_or_b64 exec, exec, s[22:23]
	v_mov_b32_e32 v28, v30
	v_mov_b32_e32 v29, v31
	v_cvt_f32_f64_e32 v34, v[26:27]
	v_readfirstlane_b32 s22, v28
	v_readfirstlane_b32 s23, v29
	s_load_dwordx2 s[22:23], s[22:23], 0xc0
	v_lshl_or_b32 v26, v33, 4, v1
	v_ashrrev_i32_e32 v27, 31, v26
	v_lshlrev_b64 v[26:27], 2, v[26:27]
	v_add_u32_e32 v32, s4, v32
	s_waitcnt lgkmcnt(0)
	v_lshl_add_u64 v[28:29], s[22:23], 0, v[26:27]
	v_add_co_u32_e32 v28, vcc, 0x2ee0000, v28
	s_nop 1
	v_addc_co_u32_e32 v29, vcc, 0, v29, vcc
	global_store_dword v[28:29], v34, off sc1
	v_mov_b32_e32 v28, v30
	v_mov_b32_e32 v29, v31
	s_nop 0
	v_readfirstlane_b32 s22, v28
	v_readfirstlane_b32 s23, v29
	s_load_dwordx2 s[22:23], s[22:23], 0xc0
	v_cvt_f32_f64_e32 v28, v[24:25]
	s_waitcnt lgkmcnt(0)
	v_lshl_add_u64 v[24:25], s[22:23], 0, v[26:27]
	v_add_co_u32_e32 v24, vcc, 0x2ee0000, v24
	s_nop 1
	v_addc_co_u32_e32 v25, vcc, 0, v25, vcc
	v_cmp_lt_i32_e32 vcc, s5, v32
	s_or_b64 s[10:11], vcc, s[10:11]
	global_store_dword v[24:25], v28, off offset:32 sc1
	s_andn2_b64 exec, exec, s[10:11]
	s_cbranch_execz .LBB0_158

.LBB0_160:
	v_mov_b32_e32 v5, v1
	v_mov_b32_e32 v9, v6
	v_add_u32_e32 v0, s4, v0
	v_readfirstlane_b32 s22, v5
	v_readfirstlane_b32 s23, v9
	s_load_dwordx2 s[22:23], s[22:23], 0x78
	v_mov_b32_e32 v9, v1
	v_cmp_lt_i32_e32 vcc, s20, v0
	s_or_b64 s[12:13], vcc, s[12:13]
	s_waitcnt lgkmcnt(0)
	v_lshl_add_u64 v[10:11], s[22:23], 0, v[2:3]
	global_load_dword v5, v[10:11], off
	v_mov_b32_e32 v10, v6
	s_waitcnt vmcnt(0)
	v_mul_f32_e64 v12, |v5|, s5
	v_readfirstlane_b32 s22, v9
	v_readfirstlane_b32 s23, v10
	s_load_dwordx2 s[22:23], s[22:23], 0xc0
	v_fma_f32 v13, |v5|, s5, -v12
	v_rndne_f32_e32 v14, v12
	v_fma_f32 v13, |v5|, s7, v13
	v_sub_f32_e32 v12, v12, v14
	v_add_f32_e32 v12, v12, v13
	v_cvt_i32_f32_e32 v14, v14
	v_exp_f32_e32 v12, v12
	s_waitcnt lgkmcnt(0)
	v_lshl_add_u64 v[10:11], s[22:23], 0, v[2:3]
	v_add_co_u32_e32 v10, vcc, 0x2f20000, v10
	v_ldexp_f32 v12, v12, v14
	s_nop 0
	v_addc_co_u32_e32 v11, vcc, 0, v11, vcc
	v_cmp_ngt_f32_e64 vcc, |v5|, s14
	v_max_f32_e32 v9, v5, v5
	v_min_f32_e32 v9, 0, v9
	v_cndmask_b32_e32 v12, 0, v12, vcc
	v_cmp_nlt_f32_e64 vcc, |v5|, s15
	v_lshl_add_u64 v[2:3], v[2:3], 0, s[10:11]
	s_nop 0
	v_cndmask_b32_e32 v26, v7, v12, vcc
	v_add_f32_e32 v5, 1.0, v26
	v_add_f32_e32 v14, -1.0, v5
	v_frexp_mant_f32_e32 v15, v5
	v_cvt_f64_f32_e32 v[12:13], v5
	v_sub_f32_e32 v16, v14, v5
	v_frexp_exp_i32_f64_e32 v12, v[12:13]
	v_cmp_gt_f32_e32 vcc, s17, v15
	v_sub_f32_e32 v14, v26, v14
	v_add_f32_e32 v13, 1.0, v16
	v_subbrev_co_u32_e32 v12, vcc, 0, v12, vcc
	v_add_f32_e32 v13, v14, v13
	v_sub_u32_e32 v14, 0, v12
	v_ldexp_f32 v5, v5, v14
	v_ldexp_f32 v13, v13, v14
	v_add_f32_e32 v14, -1.0, v5
	v_add_f32_e32 v16, 1.0, v5
	v_add_f32_e32 v15, 1.0, v14
	v_add_f32_e32 v17, -1.0, v16
	v_sub_f32_e32 v15, v5, v15
	v_sub_f32_e32 v5, v5, v17
	v_add_f32_e32 v5, v13, v5
	v_add_f32_e32 v17, v13, v15
	v_add_f32_e32 v13, v16, v5
	v_rcp_f32_e32 v20, v13
	v_add_f32_e32 v15, v14, v17
	v_sub_f32_e32 v16, v16, v13
	v_add_f32_e32 v5, v5, v16
	v_mul_f32_e32 v22, v15, v20
	v_mul_f32_e32 v16, v13, v22
	v_fma_f32 v18, v22, v13, -v16
	v_sub_f32_e32 v14, v14, v15
	v_fmac_f32_e32 v18, v22, v5
	v_add_f32_e32 v21, v17, v14
	v_add_f32_e32 v14, v16, v18
	v_sub_f32_e32 v17, v15, v14
	v_mov_b32_e32 v19, v14
	v_pk_add_f32 v[14:15], v[14:15], v[16:17] neg_lo:[0,1] neg_hi:[0,1]
	v_cvt_f32_i32_e32 v12, v12
	v_pk_add_f32 v[14:15], v[14:15], v[18:19] neg_lo:[0,1] neg_hi:[0,1]
	v_cmp_neq_f32_e32 vcc, s16, v26
	v_add_f32_e32 v15, v21, v15
	v_add_f32_e32 v14, v14, v15
	v_add_f32_e32 v15, v17, v14
	v_mul_f32_e32 v19, v20, v15
	v_mul_f32_e32 v16, v13, v19
	v_fma_f32 v18, v19, v13, -v16
	v_sub_f32_e32 v17, v17, v15
	v_fmac_f32_e32 v18, v19, v5
	v_add_f32_e32 v21, v14, v17
	v_add_f32_e32 v23, v22, v19
	v_add_f32_e32 v14, v16, v18
	v_sub_f32_e32 v13, v23, v22
	v_sub_f32_e32 v17, v15, v14
	v_sub_f32_e32 v5, v19, v13
	v_mov_b32_e32 v19, v14
	v_pk_add_f32 v[14:15], v[14:15], v[16:17] neg_lo:[0,1] neg_hi:[0,1]
	s_nop 0
	v_pk_add_f32 v[14:15], v[14:15], v[18:19] neg_lo:[0,1] neg_hi:[0,1]
	s_nop 0
	v_add_f32_e32 v13, v21, v15
	v_add_f32_e32 v13, v14, v13
	v_add_f32_e32 v13, v17, v13
	v_mul_f32_e32 v13, v20, v13
	v_add_f32_e32 v5, v5, v13
	v_add_f32_e32 v13, v23, v5
	v_mul_f32_e32 v14, v13, v13
	v_sub_f32_e32 v16, v13, v23
	v_fmamk_f32 v17, v14, 0x3e9b6dac, v8
	v_ldexp_f32 v15, v13, 1
	v_sub_f32_e32 v16, v5, v16
	v_mul_f32_e32 v13, v13, v14
	v_fmaak_f32 v5, v14, v17, 0x3f2aaada
	v_ldexp_f32 v19, v16, 1
	v_pk_mul_f32 v[16:17], v[12:13], v[4:5]
	s_nop 0
	v_fma_f32 v14, v12, s18, -v16
	v_fmac_f32_e32 v14, 0xb102e308, v12
	v_pk_add_f32 v[12:13], v[16:17], v[14:15]
	v_mov_b32_e32 v18, v16
	v_sub_f32_e32 v5, v13, v15
	v_sub_f32_e32 v5, v17, v5
	v_add_f32_e32 v19, v19, v5
	v_pk_add_f32 v[20:21], v[12:13], v[16:17] neg_lo:[0,1] neg_hi:[0,1]
	v_pk_add_f32 v[16:17], v[12:13], v[18:19]
	v_mov_b32_e32 v15, v12
	v_mov_b32_e32 v21, v17
	v_pk_add_f32 v[24:25], v[14:15], v[20:21] neg_lo:[0,1] neg_hi:[0,1]
	v_pk_add_f32 v[14:15], v[14:15], v[20:21]
	v_mov_b32_e32 v23, v12
	v_pk_add_f32 v[20:21], v[14:15], v[12:13] op_sel:[1,0] op_sel_hi:[0,1] neg_lo:[0,1] neg_hi:[0,1]
	v_mov_b32_e32 v22, v19
	v_mov_b32_e32 v18, v17
	v_mov_b32_e32 v19, v15
	v_pk_mov_b32 v[12:13], v[12:13], v[20:21] op_sel:[1,0]
	v_pk_add_f32 v[16:17], v[16:17], v[20:21] op_sel_hi:[1,0] neg_lo:[0,1] neg_hi:[0,1]
	v_pk_add_f32 v[12:13], v[18:19], v[12:13] neg_lo:[0,1] neg_hi:[0,1]
	v_mov_b32_e32 v16, v24
	v_pk_add_f32 v[12:13], v[22:23], v[12:13] neg_lo:[0,1] neg_hi:[0,1]
	v_mov_b32_e32 v25, v15
	v_pk_add_f32 v[16:17], v[16:17], v[12:13]
	s_nop 0
	v_pk_add_f32 v[18:19], v[16:17], v[16:17] op_sel:[0,1] op_sel_hi:[1,0]
	s_nop 0
	v_pk_add_f32 v[14:15], v[14:15], v[18:19] op_sel:[1,0] op_sel_hi:[0,1]
	v_mov_b32_e32 v17, v14
	v_mov_b32_e32 v13, v18
	v_pk_add_f32 v[18:19], v[16:17], v[24:25] neg_lo:[0,1] neg_hi:[0,1]
	s_nop 0
	v_sub_f32_e32 v5, v16, v18
	v_pk_add_f32 v[12:13], v[12:13], v[18:19] neg_lo:[0,1] neg_hi:[0,1]
	v_sub_f32_e32 v5, v24, v5
	v_add_f32_e32 v5, v12, v5
	v_add_f32_e32 v5, v5, v13
	v_add_f32_e32 v5, v14, v5
	v_cndmask_b32_e32 v5, v7, v5, vcc
	v_cmp_lt_f32_e64 vcc, |v26|, s19
	s_nop 1
	v_cndmask_b32_e32 v5, v5, v26, vcc
	v_sub_f32_e32 v5, v9, v5
	v_mul_f32_e32 v5, 0x41000000, v5
	v_mul_f32_e32 v5, 0x3fb8aa3b, v5
	global_store_dword v[10:11], v5, off sc1
	s_andn2_b64 exec, exec, s[12:13]
	s_cbranch_execnz .LBB0_160

.LBB0_163:
	v_mov_b32_e32 v68, v82
	v_mov_b32_e32 v69, v82
	v_pk_mul_f32 v[82:83], v[60:61], v[82:83]
	v_pk_mul_f32 v[68:69], v[62:63], v[68:69]
	s_waitcnt vmcnt(0)
	v_pk_mul_f32 v[64:65], v[82:83], v[64:65]
	v_pk_mul_f32 v[66:67], v[68:69], v[66:67]
	v_cvt_pk_bf16_f32 v64, v64, v65
	s_nop 0
	v_cvt_pk_bf16_f32 v65, v66, v67
	global_store_dwordx2 v[80:81], v[64:65], off offset:1536 sc1

.LBB0_169:
	s_waitcnt lgkmcnt(0)
	v_add_f32_e32 v65, v65, v80
	v_fmamk_f32 v65, v65, 0x3a800000, v91
	v_rsq_f32_e32 v82, v65
	s_ashr_i32 s17, s16, 31
	s_lshl_b64 s[22:23], s[16:17], 11
	v_lshl_add_u64 v[80:81], v[76:77], 0, s[22:23]
	v_pk_mul_f32 v[92:93], v[0:1], v[82:83] op_sel_hi:[1,0]
	v_pk_mul_f32 v[84:85], v[2:3], v[82:83] op_sel_hi:[1,0]
	s_waitcnt vmcnt(0)
	v_pk_mul_f32 v[66:67], v[92:93], v[66:67]
	v_pk_mul_f32 v[68:69], v[84:85], v[68:69]
	v_cvt_pk_bf16_f32 v66, v66, v67
	s_and_b64 vcc, exec, s[4:5]
	v_cvt_pk_bf16_f32 v67, v68, v69
	global_store_dwordx2 v[80:81], v[66:67], off sc1
	v_mov_b32_e32 v65, 1.0
	v_mov_b32_e32 v66, 1.0
	v_mov_b32_e32 v67, 1.0
	s_cbranch_vccnz .LBB0_171
	global_load_dwordx4 v[64:67], v[78:79], off offset:1024
.LBB0_171:
	v_mov_b32_e32 v83, v82
	v_mov_b32_e32 v84, v82
	v_mov_b32_e32 v85, v82
	v_pk_mul_f32 v[92:93], v[4:5], v[82:83]
	v_pk_mul_f32 v[68:69], v[6:7], v[84:85]
	s_waitcnt vmcnt(0)
	v_pk_mul_f32 v[64:65], v[92:93], v[64:65]
	v_pk_mul_f32 v[66:67], v[68:69], v[66:67]
	v_cvt_pk_bf16_f32 v64, v64, v65
	s_and_b64 vcc, exec, s[4:5]
	v_cvt_pk_bf16_f32 v65, v66, v67
	global_store_dwordx2 v[80:81], v[64:65], off offset:512 sc1
	v_mov_b32_e32 v64, 1.0
	v_mov_b32_e32 v66, 1.0
	v_mov_b32_e32 v67, 1.0
	v_mov_b32_e32 v68, 1.0
	v_mov_b32_e32 v69, 1.0
	s_cbranch_vccnz .LBB0_173
	global_load_dwordx4 v[66:69], v[78:79], off offset:2048
.LBB0_173:
	v_pk_mul_f32 v[92:93], v[8:9], v[82:83]
	v_pk_mul_f32 v[84:85], v[10:11], v[84:85]
	s_waitcnt vmcnt(0)
	v_pk_mul_f32 v[66:67], v[92:93], v[66:67]
	v_pk_mul_f32 v[68:69], v[84:85], v[68:69]
	v_cvt_pk_bf16_f32 v66, v66, v67
	s_and_b64 vcc, exec, s[4:5]
	v_cvt_pk_bf16_f32 v67, v68, v69
	global_store_dwordx2 v[80:81], v[66:67], off offset:1024 sc1
	v_mov_b32_e32 v65, 1.0
	v_mov_b32_e32 v66, 1.0
	v_mov_b32_e32 v67, 1.0
	s_cbranch_vccnz .LBB0_175
	global_load_dwordx4 v[64:67], v[78:79], off offset:3072
.LBB0_175:
	v_pk_mul_f32 v[68:69], v[18:19], v[18:19]
	v_pk_mul_f32 v[84:85], v[16:17], v[16:17]
	s_and_b64 vcc, exec, s[4:5]
	v_pk_mov_b32 v[92:93], v[84:85], v[68:69] op_sel:[1,0]
	v_mov_b32_e32 v85, v69
	v_pk_add_f32 v[68:69], v[92:93], v[84:85]
	v_pk_mul_f32 v[84:85], v[22:23], v[22:23]
	v_pk_add_f32 v[68:69], v[68:69], v[68:69] op_sel_hi:[0,1]
	v_pk_mul_f32 v[92:93], v[20:21], v[20:21]
	v_mul_f32_e32 v68, v24, v24
	v_pk_mov_b32 v[94:95], v[92:93], v[84:85] op_sel:[1,0]
	v_mov_b32_e32 v93, v85
	v_pk_add_f32 v[84:85], v[94:95], v[92:93]
	v_pk_fma_f32 v[92:93], v[24:25], v[24:25], v[68:69] op_sel_hi:[1,1,0]
	v_mul_f32_e32 v68, v26, v26
	v_pk_add_f32 v[84:85], v[84:85], v[84:85] op_sel_hi:[0,1]
	v_pk_fma_f32 v[94:95], v[26:27], v[26:27], v[68:69] op_sel_hi:[1,1,0]
	v_mul_f32_e32 v92, v28, v28
	v_mul_f32_e32 v94, v29, v29
	v_mul_f32_e32 v68, v30, v30
	v_mul_f32_e32 v84, v31, v31
	v_pk_add_f32 v[92:93], v[92:93], v[94:95]
	v_pk_add_f32 v[68:69], v[68:69], v[84:85]
	s_nop 0
	v_pk_add_f32 v[68:69], v[92:93], v[68:69]
	s_nop 0
	v_add_f32_e32 v68, v68, v69
	ds_bpermute_b32 v69, v71, v68
	s_waitcnt lgkmcnt(0)
	v_add_f32_e32 v68, v68, v69
	ds_bpermute_b32 v69, v73, v68
	s_waitcnt lgkmcnt(0)
	v_add_f32_e32 v69, v68, v69
	ds_bpermute_b32 v84, v87, v69
	v_mov_b32_e32 v68, v82
	s_waitcnt lgkmcnt(0)
	v_add_f32_e32 v84, v69, v84
	ds_bpermute_b32 v85, v88, v84
	v_mov_b32_e32 v69, v82
	v_pk_mul_f32 v[68:69], v[14:15], v[68:69]
	v_pk_mul_f32 v[82:83], v[12:13], v[82:83]
	s_waitcnt vmcnt(0)
	v_pk_mul_f32 v[66:67], v[68:69], v[66:67]
	s_waitcnt lgkmcnt(0)
	v_add_f32_e32 v68, v84, v85
	ds_bpermute_b32 v69, v89, v68
	v_pk_mul_f32 v[64:65], v[82:83], v[64:65]
	s_nop 0
	v_cvt_pk_bf16_f32 v64, v64, v65
	v_cvt_pk_bf16_f32 v65, v66, v67
	global_store_dwordx2 v[80:81], v[64:65], off offset:1536 sc1
	s_waitcnt lgkmcnt(0)
	v_add_f32_e32 v65, v68, v69
	ds_bpermute_b32 v80, v90, v65
	v_mov_b32_e32 v64, 1.0
	v_mov_b32_e32 v66, 1.0
	v_mov_b32_e32 v67, 1.0
	v_mov_b32_e32 v68, 1.0
	v_mov_b32_e32 v69, 1.0
	s_cbranch_vccnz .LBB0_177
	global_load_dwordx4 v[66:69], v[78:79], off
.LBB0_177:
	s_waitcnt lgkmcnt(0)
	v_add_f32_e32 v65, v65, v80
	v_fmamk_f32 v65, v65, 0x3a800000, v91
	v_rsq_f32_e32 v82, v65
	s_ashr_i32 s9, s8, 31
	s_lshl_b64 s[22:23], s[8:9], 11
	v_lshl_add_u64 v[80:81], v[76:77], 0, s[22:23]
	v_pk_mul_f32 v[92:93], v[16:17], v[82:83] op_sel_hi:[1,0]
	v_pk_mul_f32 v[84:85], v[18:19], v[82:83] op_sel_hi:[1,0]
	s_waitcnt vmcnt(0)
	v_pk_mul_f32 v[66:67], v[92:93], v[66:67]
	v_pk_mul_f32 v[68:69], v[84:85], v[68:69]
	v_cvt_pk_bf16_f32 v66, v66, v67
	s_and_b64 vcc, exec, s[4:5]
	v_cvt_pk_bf16_f32 v67, v68, v69
	global_store_dwordx2 v[80:81], v[66:67], off sc1
	v_mov_b32_e32 v65, 1.0
	v_mov_b32_e32 v66, 1.0
	v_mov_b32_e32 v67, 1.0
	s_cbranch_vccnz .LBB0_179
	global_load_dwordx4 v[64:67], v[78:79], off offset:1024
.LBB0_179:
	v_mov_b32_e32 v83, v82
	v_mov_b32_e32 v84, v82
	v_mov_b32_e32 v85, v82
	v_pk_mul_f32 v[92:93], v[20:21], v[82:83]
	v_pk_mul_f32 v[68:69], v[22:23], v[84:85]
	s_waitcnt vmcnt(0)
	v_pk_mul_f32 v[64:65], v[92:93], v[64:65]
	v_pk_mul_f32 v[66:67], v[68:69], v[66:67]
	v_cvt_pk_bf16_f32 v64, v64, v65
	s_and_b64 vcc, exec, s[4:5]
	v_cvt_pk_bf16_f32 v65, v66, v67
	global_store_dwordx2 v[80:81], v[64:65], off offset:512 sc1
	v_mov_b32_e32 v64, 1.0
	v_mov_b32_e32 v66, 1.0
	v_mov_b32_e32 v67, 1.0
	v_mov_b32_e32 v68, 1.0
	v_mov_b32_e32 v69, 1.0
	s_cbranch_vccnz .LBB0_181
	global_load_dwordx4 v[66:69], v[78:79], off offset:2048
.LBB0_181:
	v_pk_mul_f32 v[92:93], v[24:25], v[82:83]
	v_pk_mul_f32 v[84:85], v[26:27], v[84:85]
	s_waitcnt vmcnt(0)
	v_pk_mul_f32 v[66:67], v[92:93], v[66:67]
	v_pk_mul_f32 v[68:69], v[84:85], v[68:69]
	v_cvt_pk_bf16_f32 v66, v66, v67
	s_and_b64 vcc, exec, s[4:5]
	v_cvt_pk_bf16_f32 v67, v68, v69
	global_store_dwordx2 v[80:81], v[66:67], off offset:1024 sc1
	v_mov_b32_e32 v65, 1.0
	v_mov_b32_e32 v66, 1.0
	v_mov_b32_e32 v67, 1.0
	s_cbranch_vccnz .LBB0_183
	global_load_dwordx4 v[64:67], v[78:79], off offset:3072
.LBB0_183:
	s_add_i32 s22, s7, s15
	v_mov_b32_e32 v68, v82
	v_mov_b32_e32 v69, v82
	v_pk_mul_f32 v[82:83], v[28:29], v[82:83]
	s_cmpk_gt_i32 s22, 0x7ff
	v_pk_mul_f32 v[68:69], v[30:31], v[68:69]
	s_waitcnt vmcnt(0)
	v_pk_mul_f32 v[64:65], v[82:83], v[64:65]
	v_pk_mul_f32 v[66:67], v[68:69], v[66:67]
	v_cvt_pk_bf16_f32 v64, v64, v65
	s_nop 0
	v_cvt_pk_bf16_f32 v65, v66, v67
	global_store_dwordx2 v[80:81], v[64:65], off offset:1536 sc1
	s_cbranch_scc0 .LBB0_185
	s_andn2_b64 vcc, exec, s[20:21]
	s_cbranch_vccnz .LBB0_164
	s_branch .LBB0_186

.LBB0_188:
	s_waitcnt lgkmcnt(0)
	v_add_f32_e32 v65, v65, v80
	v_fmamk_f32 v65, v65, 0x3a800000, v91
	v_rsq_f32_e32 v82, v65
	s_ashr_i32 s15, s14, 31
	s_lshl_b64 s[20:21], s[14:15], 11
	v_lshl_add_u64 v[80:81], v[76:77], 0, s[20:21]
	v_pk_mul_f32 v[92:93], v[32:33], v[82:83] op_sel_hi:[1,0]
	v_pk_mul_f32 v[84:85], v[34:35], v[82:83] op_sel_hi:[1,0]
	s_waitcnt vmcnt(0)
	v_pk_mul_f32 v[66:67], v[92:93], v[66:67]
	v_pk_mul_f32 v[68:69], v[84:85], v[68:69]
	v_cvt_pk_bf16_f32 v66, v66, v67
	s_and_b64 vcc, exec, s[4:5]
	v_cvt_pk_bf16_f32 v67, v68, v69
	global_store_dwordx2 v[80:81], v[66:67], off sc1
	v_mov_b32_e32 v65, 1.0
	v_mov_b32_e32 v66, 1.0
	v_mov_b32_e32 v67, 1.0
	s_cbranch_vccnz .LBB0_190
	global_load_dwordx4 v[64:67], v[78:79], off offset:1024
.LBB0_190:
	v_mov_b32_e32 v83, v82
	v_mov_b32_e32 v84, v82
	v_mov_b32_e32 v85, v82
	v_pk_mul_f32 v[92:93], v[36:37], v[82:83]
	v_pk_mul_f32 v[68:69], v[38:39], v[84:85]
	s_waitcnt vmcnt(0)
	v_pk_mul_f32 v[64:65], v[92:93], v[64:65]
	v_pk_mul_f32 v[66:67], v[68:69], v[66:67]
	v_cvt_pk_bf16_f32 v64, v64, v65
	s_and_b64 vcc, exec, s[4:5]
	v_cvt_pk_bf16_f32 v65, v66, v67
	global_store_dwordx2 v[80:81], v[64:65], off offset:512 sc1
	v_mov_b32_e32 v64, 1.0
	v_mov_b32_e32 v66, 1.0
	v_mov_b32_e32 v67, 1.0
	v_mov_b32_e32 v68, 1.0
	v_mov_b32_e32 v69, 1.0
	s_cbranch_vccnz .LBB0_192
	global_load_dwordx4 v[66:69], v[78:79], off offset:2048
.LBB0_192:
	v_pk_mul_f32 v[92:93], v[40:41], v[82:83]
	v_pk_mul_f32 v[84:85], v[42:43], v[84:85]
	s_waitcnt vmcnt(0)
	v_pk_mul_f32 v[66:67], v[92:93], v[66:67]
	v_pk_mul_f32 v[68:69], v[84:85], v[68:69]
	v_cvt_pk_bf16_f32 v66, v66, v67
	s_and_b64 vcc, exec, s[4:5]
	v_cvt_pk_bf16_f32 v67, v68, v69
	global_store_dwordx2 v[80:81], v[66:67], off offset:1024 sc1
	v_mov_b32_e32 v65, 1.0
	v_mov_b32_e32 v66, 1.0
	v_mov_b32_e32 v67, 1.0
	s_cbranch_vccnz .LBB0_194
	global_load_dwordx4 v[64:67], v[78:79], off offset:3072
.LBB0_194:
	v_pk_mul_f32 v[68:69], v[50:51], v[50:51]
	v_pk_mul_f32 v[84:85], v[48:49], v[48:49]
	s_and_b64 vcc, exec, s[4:5]
	v_pk_mov_b32 v[92:93], v[84:85], v[68:69] op_sel:[1,0]
	v_mov_b32_e32 v85, v69
	v_pk_add_f32 v[68:69], v[92:93], v[84:85]
	v_pk_mul_f32 v[84:85], v[54:55], v[54:55]
	v_pk_add_f32 v[68:69], v[68:69], v[68:69] op_sel_hi:[0,1]
	v_pk_mul_f32 v[92:93], v[52:53], v[52:53]
	v_mul_f32_e32 v68, v56, v56
	v_pk_mov_b32 v[94:95], v[92:93], v[84:85] op_sel:[1,0]
	v_mov_b32_e32 v93, v85
	v_pk_add_f32 v[84:85], v[94:95], v[92:93]
	v_pk_fma_f32 v[92:93], v[56:57], v[56:57], v[68:69] op_sel_hi:[1,1,0]
	v_mul_f32_e32 v68, v58, v58
	v_pk_add_f32 v[84:85], v[84:85], v[84:85] op_sel_hi:[0,1]
	v_pk_fma_f32 v[94:95], v[58:59], v[58:59], v[68:69] op_sel_hi:[1,1,0]
	v_mul_f32_e32 v92, v60, v60
	v_mul_f32_e32 v94, v61, v61
	v_mul_f32_e32 v84, v62, v62
	v_mul_f32_e32 v68, v63, v63
	v_pk_add_f32 v[92:93], v[92:93], v[94:95]
	v_pk_add_f32 v[68:69], v[84:85], v[68:69]
	s_nop 0
	v_pk_add_f32 v[68:69], v[92:93], v[68:69]
	s_nop 0
	v_add_f32_e32 v68, v68, v69
	ds_bpermute_b32 v69, v71, v68
	s_waitcnt lgkmcnt(0)
	v_add_f32_e32 v68, v68, v69
	ds_bpermute_b32 v69, v73, v68
	s_waitcnt lgkmcnt(0)
	v_add_f32_e32 v69, v68, v69
	ds_bpermute_b32 v84, v87, v69
	v_mov_b32_e32 v68, v82
	s_waitcnt lgkmcnt(0)
	v_add_f32_e32 v84, v69, v84
	ds_bpermute_b32 v85, v88, v84
	v_mov_b32_e32 v69, v82
	v_pk_mul_f32 v[68:69], v[46:47], v[68:69]
	v_pk_mul_f32 v[82:83], v[44:45], v[82:83]
	s_waitcnt vmcnt(0)
	v_pk_mul_f32 v[66:67], v[68:69], v[66:67]
	s_waitcnt lgkmcnt(0)
	v_add_f32_e32 v68, v84, v85
	ds_bpermute_b32 v69, v89, v68
	v_pk_mul_f32 v[64:65], v[82:83], v[64:65]
	s_nop 0
	v_cvt_pk_bf16_f32 v64, v64, v65
	v_cvt_pk_bf16_f32 v65, v66, v67
	global_store_dwordx2 v[80:81], v[64:65], off offset:1536 sc1
	s_waitcnt lgkmcnt(0)
	v_add_f32_e32 v65, v68, v69
	ds_bpermute_b32 v80, v90, v65
	v_mov_b32_e32 v64, 1.0
	v_mov_b32_e32 v66, 1.0
	v_mov_b32_e32 v67, 1.0
	v_mov_b32_e32 v68, 1.0
	v_mov_b32_e32 v69, 1.0
	s_cbranch_vccnz .LBB0_196
	global_load_dwordx4 v[66:69], v[78:79], off
.LBB0_196:
	s_waitcnt lgkmcnt(0)
	v_add_f32_e32 v65, v65, v80
	v_fmamk_f32 v65, v65, 0x3a800000, v91
	v_rsq_f32_e32 v82, v65
	s_ashr_i32 s13, s12, 31
	s_lshl_b64 s[20:21], s[12:13], 11
	v_lshl_add_u64 v[80:81], v[76:77], 0, s[20:21]
	v_pk_mul_f32 v[92:93], v[48:49], v[82:83] op_sel_hi:[1,0]
	v_pk_mul_f32 v[84:85], v[50:51], v[82:83] op_sel_hi:[1,0]
	s_waitcnt vmcnt(0)
	v_pk_mul_f32 v[66:67], v[92:93], v[66:67]
	v_pk_mul_f32 v[68:69], v[84:85], v[68:69]
	v_cvt_pk_bf16_f32 v66, v66, v67
	s_and_b64 vcc, exec, s[4:5]
	v_cvt_pk_bf16_f32 v67, v68, v69
	global_store_dwordx2 v[80:81], v[66:67], off sc1
	v_mov_b32_e32 v65, 1.0
	v_mov_b32_e32 v66, 1.0
	v_mov_b32_e32 v67, 1.0
	s_cbranch_vccnz .LBB0_198
	global_load_dwordx4 v[64:67], v[78:79], off offset:1024
.LBB0_198:
	v_mov_b32_e32 v83, v82
	v_mov_b32_e32 v84, v82
	v_mov_b32_e32 v85, v82
	v_pk_mul_f32 v[92:93], v[52:53], v[82:83]
	v_pk_mul_f32 v[68:69], v[54:55], v[84:85]
	s_waitcnt vmcnt(0)
	v_pk_mul_f32 v[64:65], v[92:93], v[64:65]
	v_pk_mul_f32 v[66:67], v[68:69], v[66:67]
	v_cvt_pk_bf16_f32 v64, v64, v65
	s_and_b64 vcc, exec, s[4:5]
	v_cvt_pk_bf16_f32 v65, v66, v67
	global_store_dwordx2 v[80:81], v[64:65], off offset:512 sc1
	v_mov_b32_e32 v64, 1.0
	v_mov_b32_e32 v66, 1.0
	v_mov_b32_e32 v67, 1.0
	v_mov_b32_e32 v68, 1.0
	v_mov_b32_e32 v69, 1.0
	s_cbranch_vccnz .LBB0_200
	global_load_dwordx4 v[66:69], v[78:79], off offset:2048
.LBB0_200:
	v_pk_mul_f32 v[92:93], v[56:57], v[82:83]
	v_pk_mul_f32 v[84:85], v[58:59], v[84:85]
	s_waitcnt vmcnt(0)
	v_pk_mul_f32 v[66:67], v[92:93], v[66:67]
	v_pk_mul_f32 v[68:69], v[84:85], v[68:69]
	v_cvt_pk_bf16_f32 v66, v66, v67
	s_and_b64 vcc, exec, s[4:5]
	v_cvt_pk_bf16_f32 v67, v68, v69
	global_store_dwordx2 v[80:81], v[66:67], off offset:1024 sc1
	v_mov_b32_e32 v65, 1.0
	v_mov_b32_e32 v66, 1.0
	v_mov_b32_e32 v67, 1.0
	s_cbranch_vccnz .LBB0_163
	global_load_dwordx4 v[64:67], v[78:79], off offset:3072
	s_branch .LBB0_163

.LBB0_208:
	s_waitcnt vmcnt(7)
	v_mul_f32_e32 v70, v1, v1
	s_waitcnt lgkmcnt(0)
	v_mul_f32_e32 v71, v3, v3
	v_fmac_f32_e32 v70, v0, v0
	v_fmac_f32_e32 v71, v2, v2
	v_add_f32_e32 v70, v70, v71
	s_waitcnt vmcnt(6)
	v_mul_f32_e32 v71, v5, v5
	v_mul_f32_e32 v72, v7, v7
	v_fmac_f32_e32 v71, v4, v4
	v_fmac_f32_e32 v72, v6, v6
	v_add_f32_e32 v71, v71, v72
	v_add_f32_e32 v70, v70, v71
	s_waitcnt vmcnt(5)
	v_mul_f32_e32 v71, v9, v9
	v_mul_f32_e32 v72, v11, v11
	v_fmac_f32_e32 v71, v8, v8
	v_fmac_f32_e32 v72, v10, v10
	v_add_f32_e32 v71, v71, v72
	v_add_f32_e32 v70, v71, v70
	s_waitcnt vmcnt(4)
	v_mul_f32_e32 v71, v13, v13
	v_mul_f32_e32 v72, v15, v15
	v_fmac_f32_e32 v71, v12, v12
	v_fmac_f32_e32 v72, v14, v14
	v_add_f32_e32 v71, v71, v72
	v_add_f32_e32 v71, v71, v70
	v_and_b32_e32 v70, 64, v68
	v_add_u32_e32 v78, 64, v70
	v_xor_b32_e32 v70, 1, v68
	v_cmp_lt_i32_e32 vcc, v70, v78
	s_ashr_i32 s15, s14, 31
	s_lshl_b64 s[20:21], s[14:15], 11
	v_cndmask_b32_e32 v70, v68, v70, vcc
	v_lshlrev_b32_e32 v70, 2, v70
	ds_bpermute_b32 v72, v70, v71
	v_lshl_add_u64 v[80:81], v[66:67], 0, s[20:21]
	v_cvt_pk_bf16_f32 v76, v0, v1
	v_cvt_pk_bf16_f32 v77, v2, v3
	global_store_dwordx2 v[80:81], v[76:77], off sc1
	s_waitcnt lgkmcnt(0)
	v_add_f32_e32 v72, v71, v72
	v_xor_b32_e32 v71, 2, v68
	v_cmp_lt_i32_e32 vcc, v71, v78
	v_cvt_pk_bf16_f32 v76, v4, v5
	v_cvt_pk_bf16_f32 v77, v6, v7
	global_store_dwordx2 v[80:81], v[76:77], off offset:512 sc1
	v_xor_b32_e32 v76, 32, v68
	v_cndmask_b32_e32 v71, v68, v71, vcc
	v_lshlrev_b32_e32 v71, 2, v71
	ds_bpermute_b32 v74, v71, v72
	v_cvt_pk_bf16_f32 v82, v8, v9
	v_cvt_pk_bf16_f32 v83, v10, v11
	global_store_dwordx2 v[80:81], v[82:83], off offset:1024 sc1
	v_cvt_pk_bf16_f32 v82, v12, v13
	s_waitcnt lgkmcnt(0)
	v_add_f32_e32 v74, v72, v74
	v_xor_b32_e32 v72, 4, v68
	v_cmp_lt_i32_e32 vcc, v72, v78
	v_cvt_pk_bf16_f32 v83, v14, v15
	global_store_dwordx2 v[80:81], v[82:83], off offset:1536 sc1
	s_nop 0
	v_cndmask_b32_e32 v72, v68, v72, vcc
	v_lshlrev_b32_e32 v72, 2, v72
	ds_bpermute_b32 v75, v72, v74
	s_waitcnt lgkmcnt(0)
	v_add_f32_e32 v75, v74, v75
	v_xor_b32_e32 v74, 8, v68
	v_cmp_lt_i32_e32 vcc, v74, v78
	s_nop 1
	v_cndmask_b32_e32 v74, v68, v74, vcc
	v_lshlrev_b32_e32 v74, 2, v74
	ds_bpermute_b32 v79, v74, v75
	s_waitcnt lgkmcnt(0)
	v_add_f32_e32 v79, v75, v79
	v_xor_b32_e32 v75, 16, v68
	v_cmp_lt_i32_e32 vcc, v75, v78
	s_nop 1
	v_cndmask_b32_e32 v75, v68, v75, vcc
	v_lshlrev_b32_e32 v75, 2, v75
	ds_bpermute_b32 v84, v75, v79
	v_cmp_lt_i32_e32 vcc, v76, v78
	s_waitcnt lgkmcnt(0)
	v_add_f32_e32 v77, v79, v84
	v_cndmask_b32_e32 v76, v68, v76, vcc
	v_lshlrev_b32_e32 v76, 2, v76
	ds_bpermute_b32 v78, v76, v77
	s_and_saveexec_b64 s[20:21], s[4:5]
	s_cbranch_execz .LBB0_210
	s_waitcnt lgkmcnt(0)
	v_add_f32_e32 v77, v77, v78
	v_fmamk_f32 v77, v77, 0x3a800000, v69
	v_rsq_f32_e32 v77, v77
	s_lshl_b64 s[28:29], s[14:15], 2
	s_add_u32 s28, s22, s28
	s_addc_u32 s29, s23, s29
	global_store_dword v73, v77, s[28:29] sc1
.LBB0_210:
	s_or_b64 exec, exec, s[20:21]
	s_waitcnt vmcnt(7)
	v_mul_f32_e32 v77, v17, v17
	s_waitcnt lgkmcnt(0)
	v_mul_f32_e32 v78, v19, v19
	v_fmac_f32_e32 v77, v16, v16
	v_fmac_f32_e32 v78, v18, v18
	v_add_f32_e32 v77, v77, v78
	s_waitcnt vmcnt(6)
	v_mul_f32_e32 v78, v21, v21
	v_mul_f32_e32 v79, v23, v23
	v_fmac_f32_e32 v78, v20, v20
	v_fmac_f32_e32 v79, v22, v22
	v_add_f32_e32 v78, v78, v79
	v_add_f32_e32 v77, v77, v78
	s_waitcnt vmcnt(5)
	v_mul_f32_e32 v78, v25, v25
	v_mul_f32_e32 v79, v27, v27
	v_fmac_f32_e32 v78, v24, v24
	v_fmac_f32_e32 v79, v26, v26
	v_add_f32_e32 v78, v78, v79
	v_add_f32_e32 v77, v78, v77
	s_waitcnt vmcnt(4)
	v_mul_f32_e32 v78, v29, v29
	v_mul_f32_e32 v79, v31, v31
	v_fmac_f32_e32 v78, v28, v28
	v_fmac_f32_e32 v79, v30, v30
	v_add_f32_e32 v78, v78, v79
	v_add_f32_e32 v77, v78, v77
	ds_bpermute_b32 v78, v70, v77
	s_ashr_i32 s9, s8, 31
	s_lshl_b64 s[20:21], s[8:9], 11
	v_lshl_add_u64 v[80:81], v[66:67], 0, s[20:21]
	s_waitcnt lgkmcnt(0)
	v_add_f32_e32 v77, v77, v78
	ds_bpermute_b32 v78, v71, v77
	s_waitcnt lgkmcnt(0)
	v_add_f32_e32 v77, v77, v78
	ds_bpermute_b32 v78, v72, v77
	s_waitcnt lgkmcnt(0)
	v_add_f32_e32 v77, v77, v78
	ds_bpermute_b32 v82, v74, v77
	v_cvt_pk_bf16_f32 v78, v16, v17
	v_cvt_pk_bf16_f32 v79, v18, v19
	global_store_dwordx2 v[80:81], v[78:79], off sc1
	v_cvt_pk_bf16_f32 v78, v20, v21
	s_waitcnt lgkmcnt(0)
	v_add_f32_e32 v77, v77, v82
	ds_bpermute_b32 v84, v75, v77
	v_cvt_pk_bf16_f32 v79, v22, v23
	global_store_dwordx2 v[80:81], v[78:79], off offset:512 sc1
	v_cvt_pk_bf16_f32 v82, v24, v25
	v_cvt_pk_bf16_f32 v83, v26, v27
	s_waitcnt lgkmcnt(0)
	v_add_f32_e32 v77, v77, v84
	ds_bpermute_b32 v78, v76, v77
	global_store_dwordx2 v[80:81], v[82:83], off offset:1024 sc1
	v_cvt_pk_bf16_f32 v82, v28, v29
	v_cvt_pk_bf16_f32 v83, v30, v31
	global_store_dwordx2 v[80:81], v[82:83], off offset:1536 sc1
	s_and_saveexec_b64 s[20:21], s[4:5]
	s_cbranch_execnz .LBB0_213
	s_or_b64 exec, exec, s[20:21]
	s_add_i32 s20, s24, s6
	s_cmpk_gt_i32 s20, 0x7fff
	s_cbranch_scc0 .LBB0_214

.LBB0_213:
	s_waitcnt lgkmcnt(0)
	v_add_f32_e32 v77, v77, v78
	v_fmamk_f32 v77, v77, 0x3a800000, v69
	v_rsq_f32_e32 v77, v77
	s_lshl_b64 s[28:29], s[8:9], 2
	s_add_u32 s28, s22, s28
	s_addc_u32 s29, s23, s29
	global_store_dword v73, v77, s[28:29] sc1
	s_or_b64 exec, exec, s[20:21]
	s_add_i32 s20, s24, s6
	s_cmpk_gt_i32 s20, 0x7fff
	s_cbranch_scc1 .LBB0_212

.LBB0_215:
	v_mul_f32_e32 v77, v33, v33
	s_waitcnt lgkmcnt(0)
	v_mul_f32_e32 v78, v35, v35
	v_fmac_f32_e32 v77, v32, v32
	v_fmac_f32_e32 v78, v34, v34
	v_add_f32_e32 v77, v77, v78
	v_mul_f32_e32 v78, v37, v37
	v_mul_f32_e32 v79, v39, v39
	v_fmac_f32_e32 v78, v36, v36
	v_fmac_f32_e32 v79, v38, v38
	v_add_f32_e32 v78, v78, v79
	v_add_f32_e32 v77, v78, v77
	v_mul_f32_e32 v78, v41, v41
	v_mul_f32_e32 v79, v43, v43
	v_fmac_f32_e32 v78, v40, v40
	v_fmac_f32_e32 v79, v42, v42
	v_add_f32_e32 v78, v78, v79
	v_add_f32_e32 v77, v78, v77
	v_mul_f32_e32 v78, v45, v45
	v_mul_f32_e32 v79, v47, v47
	v_fmac_f32_e32 v78, v44, v44
	v_fmac_f32_e32 v79, v46, v46
	v_add_f32_e32 v78, v78, v79
	v_add_f32_e32 v77, v78, v77
	ds_bpermute_b32 v78, v70, v77
	s_ashr_i32 s13, s12, 31
	s_lshl_b64 s[6:7], s[12:13], 11
	v_lshl_add_u64 v[80:81], v[66:67], 0, s[6:7]
	s_waitcnt lgkmcnt(0)
	v_add_f32_e32 v77, v77, v78
	ds_bpermute_b32 v78, v71, v77
	s_waitcnt lgkmcnt(0)
	v_add_f32_e32 v77, v77, v78
	ds_bpermute_b32 v78, v72, v77
	s_waitcnt lgkmcnt(0)
	v_add_f32_e32 v77, v77, v78
	ds_bpermute_b32 v82, v74, v77
	v_cvt_pk_bf16_f32 v78, v32, v33
	v_cvt_pk_bf16_f32 v79, v34, v35
	global_store_dwordx2 v[80:81], v[78:79], off sc1
	v_cvt_pk_bf16_f32 v78, v36, v37
	s_waitcnt lgkmcnt(0)
	v_add_f32_e32 v77, v77, v82
	ds_bpermute_b32 v84, v75, v77
	v_cvt_pk_bf16_f32 v79, v38, v39
	global_store_dwordx2 v[80:81], v[78:79], off offset:512 sc1
	v_cvt_pk_bf16_f32 v82, v40, v41
	v_cvt_pk_bf16_f32 v83, v42, v43
	s_waitcnt lgkmcnt(0)
	v_add_f32_e32 v77, v77, v84
	ds_bpermute_b32 v78, v76, v77
	global_store_dwordx2 v[80:81], v[82:83], off offset:1024 sc1
	v_cvt_pk_bf16_f32 v82, v44, v45
	v_cvt_pk_bf16_f32 v83, v46, v47
	global_store_dwordx2 v[80:81], v[82:83], off offset:1536 sc1
	s_and_saveexec_b64 s[6:7], s[4:5]
	s_cbranch_execz .LBB0_217
	s_waitcnt lgkmcnt(0)
	v_add_f32_e32 v77, v77, v78
	v_fmamk_f32 v77, v77, 0x3a800000, v69
	v_rsq_f32_e32 v77, v77
	s_lshl_b64 s[18:19], s[12:13], 2
	s_add_u32 s18, s22, s18
	s_addc_u32 s19, s23, s19
	global_store_dword v73, v77, s[18:19] sc1
.LBB0_217:
	s_or_b64 exec, exec, s[6:7]
	v_mul_f32_e32 v77, v49, v49
	s_waitcnt lgkmcnt(0)
	v_mul_f32_e32 v78, v51, v51
	v_fmac_f32_e32 v77, v48, v48
	v_fmac_f32_e32 v78, v50, v50
	v_add_f32_e32 v77, v77, v78
	v_mul_f32_e32 v78, v53, v53
	v_mul_f32_e32 v79, v55, v55
	v_fmac_f32_e32 v78, v52, v52
	v_fmac_f32_e32 v79, v54, v54
	v_add_f32_e32 v78, v78, v79
	v_add_f32_e32 v77, v78, v77
	v_mul_f32_e32 v78, v57, v57
	v_mul_f32_e32 v79, v59, v59
	v_fmac_f32_e32 v78, v56, v56
	v_fmac_f32_e32 v79, v58, v58
	v_add_f32_e32 v78, v78, v79
	v_add_f32_e32 v77, v78, v77
	v_mul_f32_e32 v78, v61, v61
	v_mul_f32_e32 v79, v63, v63
	v_fmac_f32_e32 v78, v60, v60
	v_fmac_f32_e32 v79, v62, v62
	v_add_f32_e32 v78, v78, v79
	v_add_f32_e32 v77, v78, v77
	ds_bpermute_b32 v70, v70, v77
	s_ashr_i32 s11, s10, 31
	s_lshl_b64 s[6:7], s[10:11], 11
	v_lshl_add_u64 v[78:79], v[66:67], 0, s[6:7]
	s_waitcnt lgkmcnt(0)
	v_add_f32_e32 v70, v77, v70
	ds_bpermute_b32 v71, v71, v70
	s_waitcnt lgkmcnt(0)
	v_add_f32_e32 v70, v70, v71
	ds_bpermute_b32 v71, v72, v70
	s_waitcnt lgkmcnt(0)
	v_add_f32_e32 v72, v70, v71
	ds_bpermute_b32 v74, v74, v72
	v_cvt_pk_bf16_f32 v70, v48, v49
	v_cvt_pk_bf16_f32 v71, v50, v51
	global_store_dwordx2 v[78:79], v[70:71], off sc1
	v_cvt_pk_bf16_f32 v70, v52, v53
	s_waitcnt lgkmcnt(0)
	v_add_f32_e32 v72, v72, v74
	ds_bpermute_b32 v77, v75, v72
	v_cvt_pk_bf16_f32 v71, v54, v55
	global_store_dwordx2 v[78:79], v[70:71], off offset:512 sc1
	v_cvt_pk_bf16_f32 v74, v56, v57
	v_cvt_pk_bf16_f32 v75, v58, v59
	s_waitcnt lgkmcnt(0)
	v_add_f32_e32 v70, v72, v77
	ds_bpermute_b32 v71, v76, v70
	global_store_dwordx2 v[78:79], v[74:75], off offset:1024 sc1
	v_cvt_pk_bf16_f32 v74, v60, v61
	v_cvt_pk_bf16_f32 v75, v62, v63
	global_store_dwordx2 v[78:79], v[74:75], off offset:1536 sc1
	s_and_saveexec_b64 s[6:7], s[4:5]
	s_cbranch_execz .LBB0_204
	s_waitcnt lgkmcnt(0)
	v_add_f32_e32 v70, v70, v71
	v_fmamk_f32 v70, v70, 0x3a800000, v69
	v_rsq_f32_e32 v70, v70
	s_lshl_b64 s[18:19], s[10:11], 2
	s_add_u32 s18, s22, s18
	s_addc_u32 s19, s23, s19
	global_store_dword v73, v70, s[18:19] sc1
	s_branch .LBB0_204
